# diff-attn FAST tile loop rewritten by hand: software-pipelined 24-MFMA-slot schedule, K/V fragment prefetch, V DMA offsets +3/+4, deferred cross-half row-sum
# speedup vs baseline: 1.0458x; 1.0458x over previous
.LBB0_318:
	v_and_b32_e32 v131, 63, v16
	v_lshlrev_b32_e32 v0, 4, v136
	v_lshlrev_b32_e32 v30, 8, v136
	v_and_b32_e32 v31, 0x70, v0
	v_or_b32_e32 v21, s4, v130
	v_bitop3_b32 v149, v21, v30, v31 bitop3:0xde
	v_or_b32_e32 v22, 32, v21
	v_bitop3_b32 v148, v22, v30, v31 bitop3:0xde
	v_or_b32_e32 v22, 64, v21
	v_bitop3_b32 v143, v22, v30, v31 bitop3:0xde
	v_or_b32_e32 v22, 0x60, v21
	v_bitop3_b32 v141, v22, v30, v31 bitop3:0xde
	v_add_u32_e32 v149, s38, v149
	v_add_u32_e32 v148, s38, v148
	v_add_u32_e32 v143, s38, v143
	v_add_u32_e32 v141, s38, v141
	v_lshlrev_b32_e32 v34, 4, v131
	v_lshlrev_b32_e32 v33, 3, v131
	v_and_b32_e32 v22, 0xc0, v34
	v_and_or_b32 v34, v33, 24, v22
	v_lshlrev_b32_e32 v26, 1, v131
	v_and_b32_e32 v30, 32, v26
	v_and_b32_e32 v33, 0x100, v33
	v_or3_b32 v140, v34, v30, v33
	v_mov_b32_e32 v151, v140
	v_add3_u32 v0, v18, v20, s45
	v_ashrrev_i32_e32 v1, 31, v0
	v_lshlrev_b64 v[0:1], 13, v[0:1]
	v_and_b32_e32 v2, 3, v16
	v_lshl_add_u64 v[0:1], s[10:11], 0, v[0:1]
	v_lshlrev_b32_e32 v2, 4, v2
	v_mov_b32_e32 v3, v129
	v_lshl_add_u64 v[0:1], v[0:1], 0, v[2:3]
	v_add_lshl_u32 v2, s44, v19, 1
	v_lshl_add_u64 v[0:1], v[0:1], 0, v[2:3]
	v_lshl_add_u64 v[132:133], s[28:29], 0, v[0:1]
	v_add_u32_e32 v0, s5, v17
	v_ashrrev_i32_e32 v1, 31, v0
	v_lshlrev_b64 v[0:1], 13, v[0:1]
	v_lshl_add_u64 v[0:1], s[10:11], 0, v[0:1]
	v_lshl_add_u64 v[0:1], v[0:1], 0, v[128:129]
	v_lshl_add_u64 v[134:135], s[28:29], 0, v[0:1]
	v_lshl_add_u64 v[132:133], v[132:133], 0, s[16:17]
	v_lshl_add_u64 v[134:135], v[134:135], 0, s[16:17]
	s_mov_b64 s[42:43], 0x5d81000
	s_mov_b64 s[46:47], 0x5dc1000
	s_mov_b32 s62, 0
	s_add_i32 s71, s41, 0x2000
	s_movk_i32 s70, 31
	v_mov_b32_e32 v0, 0
	v_mov_b32_e32 v1, 0
	v_mov_b32_e32 v2, 0
	v_mov_b32_e32 v3, 0
	v_mov_b32_e32 v4, 0
	v_mov_b32_e32 v5, 0
	v_mov_b32_e32 v6, 0
	v_mov_b32_e32 v7, 0
	v_mov_b32_e32 v8, 0
	v_mov_b32_e32 v9, 0
	v_mov_b32_e32 v10, 0
	v_mov_b32_e32 v11, 0
	v_mov_b32_e32 v12, 0
	v_mov_b32_e32 v13, 0
	v_mov_b32_e32 v14, 0
	v_mov_b32_e32 v15, 0
	v_mov_b32_e32 v16, 0
	v_mov_b32_e32 v17, 0
	v_mov_b32_e32 v18, 0
	v_mov_b32_e32 v19, 0
	v_mov_b32_e32 v20, 0
	v_mov_b32_e32 v21, 0
	v_mov_b32_e32 v22, 0
	v_mov_b32_e32 v23, 0
	v_mov_b32_e32 v24, 0
	v_mov_b32_e32 v25, 0
	v_mov_b32_e32 v26, 0
	v_mov_b32_e32 v27, 0
	v_mov_b32_e32 v28, 0
	v_mov_b32_e32 v29, 0
	v_mov_b32_e32 v30, 0
	v_mov_b32_e32 v31, 0
	v_mov_b32_e32 v32, 0
	v_mov_b32_e32 v33, 0
	v_mov_b32_e32 v34, 0
	v_mov_b32_e32 v35, 0
	v_mov_b32_e32 v36, 0
	v_mov_b32_e32 v37, 0
	v_mov_b32_e32 v38, 0
	v_mov_b32_e32 v39, 0
	v_mov_b32_e32 v40, 0
	v_mov_b32_e32 v41, 0
	v_mov_b32_e32 v42, 0
	v_mov_b32_e32 v43, 0
	v_mov_b32_e32 v44, 0
	v_mov_b32_e32 v45, 0
	v_mov_b32_e32 v46, 0
	v_mov_b32_e32 v47, 0
	v_mov_b32_e32 v48, 0
	v_mov_b32_e32 v49, 0
	v_mov_b32_e32 v50, 0
	v_mov_b32_e32 v51, 0
	v_mov_b32_e32 v52, 0
	v_mov_b32_e32 v53, 0
	v_mov_b32_e32 v54, 0
	v_mov_b32_e32 v55, 0
	v_mov_b32_e32 v56, 0
	v_mov_b32_e32 v57, 0
	v_mov_b32_e32 v58, 0
	v_mov_b32_e32 v59, 0
	v_mov_b32_e32 v60, 0
	v_mov_b32_e32 v61, 0
	v_mov_b32_e32 v62, 0
	v_mov_b32_e32 v63, 0
	v_mov_b32_e32 v234, 0
	v_mov_b32_e32 v235, 0
	s_waitcnt vmcnt(0)
	s_barrier
	ds_read_b128 v[194:197], v149 offset:0
	ds_read_b128 v[198:201], v148 offset:0
	ds_read_b128 v[202:205], v143 offset:0
	ds_read_b128 v[206:209], v141 offset:0
	ds_read_b128 v[210:213], v149 offset:8192
	ds_read_b128 v[214:217], v148 offset:8192
	ds_read_b128 v[218:221], v143 offset:8192
	ds_read_b128 v[222:225], v141 offset:8192
	s_waitcnt lgkmcnt(7)
	v_mfma_f32_32x32x16_bf16 v[64:79], v[194:197], v[124:127], 0
	s_waitcnt lgkmcnt(6)
	v_mfma_f32_32x32x16_bf16 v[64:79], v[198:201], v[120:123], v[64:79]
	s_waitcnt lgkmcnt(5)
	v_mfma_f32_32x32x16_bf16 v[64:79], v[202:205], v[116:119], v[64:79]
	s_waitcnt lgkmcnt(4)
	v_mfma_f32_32x32x16_bf16 v[64:79], v[206:209], v[112:115], v[64:79]
	s_waitcnt lgkmcnt(3)
	v_mfma_f32_32x32x16_bf16 v[80:95], v[210:213], v[124:127], 0
	s_waitcnt lgkmcnt(2)
	v_mfma_f32_32x32x16_bf16 v[80:95], v[214:217], v[120:123], v[80:95]
	s_waitcnt lgkmcnt(1)
	v_mfma_f32_32x32x16_bf16 v[80:95], v[218:221], v[116:119], v[80:95]
	s_waitcnt lgkmcnt(0)
	v_mfma_f32_32x32x16_bf16 v[80:95], v[222:225], v[112:115], v[80:95]
	s_nop 3
	v_exp_f32_e32 v64, v64
	v_exp_f32_e32 v65, v65
	ds_read_b128 v[194:197], v149 offset:16384
	v_exp_f32_e32 v66, v66
	v_exp_f32_e32 v67, v67
	v_add_f32_e32 v234, v234, v64
	ds_read_b128 v[198:201], v148 offset:16384
	v_exp_f32_e32 v68, v68
	v_exp_f32_e32 v69, v69
	v_add_f32_e32 v235, v235, v65
	v_add_f32_e32 v234, v234, v66
	ds_read_b128 v[202:205], v143 offset:16384
	v_exp_f32_e32 v70, v70
	v_exp_f32_e32 v71, v71
	v_add_f32_e32 v235, v235, v67
	v_add_f32_e32 v234, v234, v68
	ds_read_b128 v[206:209], v141 offset:16384
	v_add_f32_e32 v235, v235, v69
	v_add_f32_e32 v234, v234, v70
	v_add_f32_e32 v235, v235, v71
	v_cvt_pk_bf16_f32 v178, v64, v65
	v_cvt_pk_bf16_f32 v180, v68, v69
	ds_read_b128 v[210:213], v149 offset:24576
	v_cvt_pk_bf16_f32 v179, v66, v67
	v_cvt_pk_bf16_f32 v181, v70, v71
	v_permlane32_swap_b32_e32 v178, v180
	ds_read_b128 v[214:217], v148 offset:24576
	v_permlane32_swap_b32_e32 v179, v181
.Lda_loop:
	s_waitcnt lgkmcnt(5)
	v_mfma_f32_32x32x16_bf16 v[96:111], v[194:197], v[124:127], 0
	v_exp_f32_e32 v72, v72
	v_exp_f32_e32 v73, v73
	ds_read_b128 v[218:221], v143 offset:24576
	s_waitcnt lgkmcnt(5)
	v_mfma_f32_32x32x16_bf16 v[96:111], v[198:201], v[120:123], v[96:111]
	v_exp_f32_e32 v74, v74
	v_exp_f32_e32 v75, v75
	v_add_f32_e32 v234, v234, v72
	ds_read_b128 v[222:225], v141 offset:24576
	ds_read_b64_tr_b16 v[226:227], v151 offset:0
	ds_read_b64_tr_b16 v[228:229], v151 offset:2048
	s_waitcnt lgkmcnt(7)
	v_mfma_f32_32x32x16_bf16 v[96:111], v[202:205], v[116:119], v[96:111]
	v_exp_f32_e32 v76, v76
	v_exp_f32_e32 v77, v77
	v_add_f32_e32 v235, v235, v73
	v_add_f32_e32 v234, v234, v74
	ds_read_b64_tr_b16 v[230:231], v151 offset:512
	ds_read_b64_tr_b16 v[232:233], v151 offset:2560
	s_waitcnt lgkmcnt(8)
	v_mfma_f32_32x32x16_bf16 v[96:111], v[206:209], v[112:115], v[96:111]
	v_exp_f32_e32 v78, v78
	v_exp_f32_e32 v79, v79
	v_add_f32_e32 v235, v235, v75
	v_add_f32_e32 v234, v234, v76
	ds_read_b64_tr_b16 v[238:239], v151 offset:1024
	ds_read_b64_tr_b16 v[240:241], v151 offset:3072
	s_waitcnt lgkmcnt(9)
	v_mfma_f32_32x32x16_bf16 v[162:177], v[210:213], v[124:127], 0
	v_add_f32_e32 v235, v235, v77
	v_add_f32_e32 v234, v234, v78
	v_add_f32_e32 v235, v235, v79
	v_cvt_pk_bf16_f32 v182, v72, v73
	v_cvt_pk_bf16_f32 v184, v76, v77
	ds_read_b64_tr_b16 v[242:243], v151 offset:1536
	ds_read_b64_tr_b16 v[244:245], v151 offset:3584
	s_waitcnt lgkmcnt(10)
	v_mfma_f32_32x32x16_bf16 v[162:177], v[214:217], v[120:123], v[162:177]
	v_cvt_pk_bf16_f32 v183, v74, v75
	v_cvt_pk_bf16_f32 v185, v78, v79
	v_permlane32_swap_b32_e32 v182, v184
	ds_read_b64_tr_b16 v[246:247], v151 offset:4096
	ds_read_b64_tr_b16 v[248:249], v151 offset:6144
	v_permlane32_swap_b32_e32 v183, v185
	s_waitcnt lgkmcnt(11)
	v_mfma_f32_32x32x16_bf16 v[162:177], v[218:221], v[116:119], v[162:177]
	v_exp_f32_e32 v80, v80
	v_exp_f32_e32 v81, v81
	ds_read_b64_tr_b16 v[250:251], v151 offset:4608
	ds_read_b64_tr_b16 v[252:253], v151 offset:6656
	s_waitcnt lgkmcnt(12)
	v_mfma_f32_32x32x16_bf16 v[162:177], v[222:225], v[112:115], v[162:177]
	v_exp_f32_e32 v82, v82
	v_exp_f32_e32 v83, v83
	v_add_f32_e32 v234, v234, v80
	ds_read_b64_tr_b16 v[152:153], v151 offset:5120
	ds_read_b64_tr_b16 v[154:155], v151 offset:7168
	s_waitcnt lgkmcnt(12)
	v_mfma_f32_32x32x16_bf16 v[48:63], v[178:181], v[226:229], v[48:63]
	v_exp_f32_e32 v84, v84
	v_exp_f32_e32 v85, v85
	v_add_f32_e32 v235, v235, v81
	v_add_f32_e32 v234, v234, v82
	ds_read_b64_tr_b16 v[226:227], v151 offset:5632
	ds_read_b64_tr_b16 v[228:229], v151 offset:7680
	s_waitcnt lgkmcnt(12)
	v_mfma_f32_32x32x16_bf16 v[32:47], v[178:181], v[230:233], v[32:47]
	v_exp_f32_e32 v86, v86
	v_exp_f32_e32 v87, v87
	v_add_f32_e32 v235, v235, v83
	v_add_f32_e32 v234, v234, v84
	ds_read_b64_tr_b16 v[230:231], v151 offset:8192
	ds_read_b64_tr_b16 v[232:233], v151 offset:10240
	s_waitcnt lgkmcnt(12)
	v_mfma_f32_32x32x16_bf16 v[16:31], v[178:181], v[238:241], v[16:31]
	v_add_f32_e32 v235, v235, v85
	v_add_f32_e32 v234, v234, v86
	v_add_f32_e32 v235, v235, v87
	v_cvt_pk_bf16_f32 v186, v80, v81
	v_cvt_pk_bf16_f32 v188, v84, v85
	ds_read_b64_tr_b16 v[238:239], v151 offset:8704
	ds_read_b64_tr_b16 v[240:241], v151 offset:10752
	s_waitcnt lgkmcnt(12)
	v_mfma_f32_32x32x16_bf16 v[0:15], v[178:181], v[242:245], v[0:15]
	v_cvt_pk_bf16_f32 v187, v82, v83
	v_cvt_pk_bf16_f32 v189, v86, v87
	v_permlane32_swap_b32_e32 v186, v188
	ds_read_b64_tr_b16 v[242:243], v151 offset:9216
	ds_read_b64_tr_b16 v[244:245], v151 offset:11264
	v_permlane32_swap_b32_e32 v187, v189
	s_waitcnt lgkmcnt(12)
	v_mfma_f32_32x32x16_bf16 v[48:63], v[182:185], v[246:249], v[48:63]
	v_exp_f32_e32 v88, v88
	v_exp_f32_e32 v89, v89
	ds_read_b64_tr_b16 v[246:247], v151 offset:9728
	ds_read_b64_tr_b16 v[248:249], v151 offset:11776
	s_waitcnt lgkmcnt(12)
	v_mfma_f32_32x32x16_bf16 v[32:47], v[182:185], v[250:253], v[32:47]
	v_exp_f32_e32 v90, v90
	v_exp_f32_e32 v91, v91
	v_add_f32_e32 v234, v234, v88
	ds_read_b64_tr_b16 v[250:251], v151 offset:12288
	ds_read_b64_tr_b16 v[252:253], v151 offset:14336
	s_waitcnt lgkmcnt(12)
	v_mfma_f32_32x32x16_bf16 v[16:31], v[182:185], v[152:155], v[16:31]
	v_exp_f32_e32 v92, v92
	v_exp_f32_e32 v93, v93
	v_add_f32_e32 v235, v235, v89
	v_add_f32_e32 v234, v234, v90
	ds_read_b64_tr_b16 v[152:153], v151 offset:12800
	ds_read_b64_tr_b16 v[154:155], v151 offset:14848
	s_waitcnt lgkmcnt(12)
	v_mfma_f32_32x32x16_bf16 v[0:15], v[182:185], v[226:229], v[0:15]
	v_exp_f32_e32 v94, v94
	v_exp_f32_e32 v95, v95
	v_add_f32_e32 v235, v235, v91
	v_add_f32_e32 v234, v234, v92
	ds_read_b64_tr_b16 v[226:227], v151 offset:13312
	ds_read_b64_tr_b16 v[228:229], v151 offset:15360
	s_waitcnt lgkmcnt(12)
	v_mfma_f32_32x32x16_bf16 v[48:63], v[186:189], v[230:233], v[48:63]
	v_add_f32_e32 v235, v235, v93
	v_add_f32_e32 v234, v234, v94
	v_add_f32_e32 v235, v235, v95
	v_cvt_pk_bf16_f32 v190, v88, v89
	v_cvt_pk_bf16_f32 v192, v92, v93
	ds_read_b64_tr_b16 v[230:231], v151 offset:13824
	ds_read_b64_tr_b16 v[232:233], v151 offset:15872
	s_waitcnt lgkmcnt(12)
	v_mfma_f32_32x32x16_bf16 v[32:47], v[186:189], v[238:241], v[32:47]
	s_waitcnt vmcnt(0)
	s_barrier
	s_add_i32 s63, s62, 0xc000
	s_cmp_ge_u32 s63, 0x14000
	s_cselect_b32 s69, 0x14000, 0
	s_sub_i32 s63, s63, s69
	s_add_i32 s68, s62, 0x10000
	s_cmp_ge_u32 s68, 0x14000
	s_cselect_b32 s69, 0x14000, 0
	s_sub_i32 s68, s68, s69
	s_add_i32 s62, s62, 0x4000
	s_cmp_ge_u32 s62, 0x14000
	s_cselect_b32 s69, 0x14000, 0
	s_sub_i32 s62, s62, s69
	v_add_u32_e32 v151, s62, v140
	v_cvt_pk_bf16_f32 v191, v90, v91
	v_cvt_pk_bf16_f32 v193, v94, v95
	v_permlane32_swap_b32_e32 v190, v192
	s_nop 0
	v_permlane32_swap_b32_e32 v191, v193
	s_add_i32 m0, s41, s63
	v_lshl_add_u64 v[146:147], v[132:133], 0, s[42:43]
	global_load_lds_dwordx4 v[146:147], off
	s_waitcnt lgkmcnt(10)
	v_mfma_f32_32x32x16_bf16 v[16:31], v[186:189], v[242:245], v[16:31]
	v_exp_f32_e32 v96, v96
	v_exp_f32_e32 v97, v97
	ds_read_b128 v[194:197], v149 offset:32768
	s_add_i32 m0, s71, s63
	v_lshl_add_u64 v[254:255], v[132:133], 0, s[46:47]
	global_load_lds_dwordx4 v[254:255], off
	s_waitcnt lgkmcnt(9)
	v_mfma_f32_32x32x16_bf16 v[0:15], v[186:189], v[246:249], v[0:15]
	v_exp_f32_e32 v98, v98
	v_exp_f32_e32 v99, v99
	v_add_f32_e32 v234, v234, v96
	ds_read_b128 v[198:201], v148 offset:32768
	s_add_i32 m0, s40, 0x0
	v_lshl_add_u64 v[146:147], v[134:135], 0, s[84:85]
	global_load_lds_dwordx4 v[146:147], off
	s_waitcnt lgkmcnt(8)
	v_mfma_f32_32x32x16_bf16 v[48:63], v[190:193], v[250:253], v[48:63]
	v_exp_f32_e32 v100, v100
	v_exp_f32_e32 v101, v101
	v_add_f32_e32 v235, v235, v97
	v_add_f32_e32 v234, v234, v98
	ds_read_b128 v[202:205], v143 offset:32768
	s_add_i32 m0, s40, 0x2000
	v_lshl_add_u64 v[254:255], v[134:135], 0, s[86:87]
	global_load_lds_dwordx4 v[254:255], off
	s_waitcnt lgkmcnt(7)
	v_mfma_f32_32x32x16_bf16 v[32:47], v[190:193], v[152:155], v[32:47]
	v_exp_f32_e32 v102, v102
	v_exp_f32_e32 v103, v103
	v_add_f32_e32 v235, v235, v99
	v_add_f32_e32 v234, v234, v100
	ds_read_b128 v[206:209], v141 offset:32768
	s_add_i32 m0, s41, s68
	v_lshl_add_u64 v[146:147], v[132:133], 0, s[88:89]
	global_load_lds_dwordx4 v[146:147], off
	s_waitcnt lgkmcnt(6)
	v_mfma_f32_32x32x16_bf16 v[16:31], v[190:193], v[226:229], v[16:31]
	v_add_f32_e32 v235, v235, v101
	v_add_f32_e32 v234, v234, v102
	v_add_f32_e32 v235, v235, v103
	v_cvt_pk_bf16_f32 v178, v96, v97
	v_cvt_pk_bf16_f32 v180, v100, v101
	ds_read_b128 v[210:213], v149 offset:40960
	s_add_i32 m0, s71, s68
	v_lshl_add_u64 v[254:255], v[132:133], 0, s[90:91]
	global_load_lds_dwordx4 v[254:255], off
	s_waitcnt lgkmcnt(5)
	v_mfma_f32_32x32x16_bf16 v[0:15], v[190:193], v[230:233], v[0:15]
	v_cvt_pk_bf16_f32 v179, v98, v99
	v_cvt_pk_bf16_f32 v181, v102, v103
	v_permlane32_swap_b32_e32 v178, v180
	ds_read_b128 v[214:217], v148 offset:40960
	v_permlane32_swap_b32_e32 v179, v181
	s_add_i32 m0, s40, 0x4000
	v_lshl_add_u64 v[146:147], v[134:135], 0, s[92:93]
	global_load_lds_dwordx4 v[146:147], off
	s_add_i32 m0, s40, 0x6000
	v_lshl_add_u64 v[254:255], v[134:135], 0, s[94:95]
	global_load_lds_dwordx4 v[254:255], off
	v_lshl_add_u64 v[132:133], v[132:133], 0, s[12:13]
	v_lshl_add_u64 v[134:135], v[134:135], 0, s[12:13]
	s_waitcnt lgkmcnt(5)
	v_mfma_f32_32x32x16_bf16 v[64:79], v[194:197], v[124:127], 0
	v_exp_f32_e32 v104, v104
	v_exp_f32_e32 v105, v105
	ds_read_b128 v[218:221], v143 offset:40960
	s_waitcnt lgkmcnt(5)
	v_mfma_f32_32x32x16_bf16 v[64:79], v[198:201], v[120:123], v[64:79]
	v_exp_f32_e32 v106, v106
	v_exp_f32_e32 v107, v107
	v_add_f32_e32 v234, v234, v104
	ds_read_b128 v[222:225], v141 offset:40960
	ds_read_b64_tr_b16 v[226:227], v151 offset:0
	ds_read_b64_tr_b16 v[228:229], v151 offset:2048
	s_waitcnt lgkmcnt(7)
	v_mfma_f32_32x32x16_bf16 v[64:79], v[202:205], v[116:119], v[64:79]
	v_exp_f32_e32 v108, v108
	v_exp_f32_e32 v109, v109
	v_add_f32_e32 v235, v235, v105
	v_add_f32_e32 v234, v234, v106
	ds_read_b64_tr_b16 v[230:231], v151 offset:512
	ds_read_b64_tr_b16 v[232:233], v151 offset:2560
	s_waitcnt lgkmcnt(8)
	v_mfma_f32_32x32x16_bf16 v[64:79], v[206:209], v[112:115], v[64:79]
	v_exp_f32_e32 v110, v110
	v_exp_f32_e32 v111, v111
	v_add_f32_e32 v235, v235, v107
	v_add_f32_e32 v234, v234, v108
	ds_read_b64_tr_b16 v[238:239], v151 offset:1024
	ds_read_b64_tr_b16 v[240:241], v151 offset:3072
	s_waitcnt lgkmcnt(9)
	v_mfma_f32_32x32x16_bf16 v[80:95], v[210:213], v[124:127], 0
	v_add_f32_e32 v235, v235, v109
	v_add_f32_e32 v234, v234, v110
	v_add_f32_e32 v235, v235, v111
	v_cvt_pk_bf16_f32 v182, v104, v105
	v_cvt_pk_bf16_f32 v184, v108, v109
	ds_read_b64_tr_b16 v[242:243], v151 offset:1536
	ds_read_b64_tr_b16 v[244:245], v151 offset:3584
	s_waitcnt lgkmcnt(10)
	v_mfma_f32_32x32x16_bf16 v[80:95], v[214:217], v[120:123], v[80:95]
	v_cvt_pk_bf16_f32 v183, v106, v107
	v_cvt_pk_bf16_f32 v185, v110, v111
	v_permlane32_swap_b32_e32 v182, v184
	ds_read_b64_tr_b16 v[246:247], v151 offset:4096
	ds_read_b64_tr_b16 v[248:249], v151 offset:6144
	v_permlane32_swap_b32_e32 v183, v185
	s_waitcnt lgkmcnt(11)
	v_mfma_f32_32x32x16_bf16 v[80:95], v[218:221], v[116:119], v[80:95]
	v_exp_f32_e32 v162, v162
	v_exp_f32_e32 v163, v163
	ds_read_b64_tr_b16 v[250:251], v151 offset:4608
	ds_read_b64_tr_b16 v[252:253], v151 offset:6656
	s_waitcnt lgkmcnt(12)
	v_mfma_f32_32x32x16_bf16 v[80:95], v[222:225], v[112:115], v[80:95]
	v_exp_f32_e32 v164, v164
	v_exp_f32_e32 v165, v165
	v_add_f32_e32 v234, v234, v162
	ds_read_b64_tr_b16 v[152:153], v151 offset:5120
	ds_read_b64_tr_b16 v[154:155], v151 offset:7168
	s_waitcnt lgkmcnt(12)
	v_mfma_f32_32x32x16_bf16 v[48:63], v[178:181], v[226:229], v[48:63]
	v_exp_f32_e32 v166, v166
	v_exp_f32_e32 v167, v167
	v_add_f32_e32 v235, v235, v163
	v_add_f32_e32 v234, v234, v164
	ds_read_b64_tr_b16 v[226:227], v151 offset:5632
	ds_read_b64_tr_b16 v[228:229], v151 offset:7680
	s_waitcnt lgkmcnt(12)
	v_mfma_f32_32x32x16_bf16 v[32:47], v[178:181], v[230:233], v[32:47]
	v_exp_f32_e32 v168, v168
	v_exp_f32_e32 v169, v169
	v_add_f32_e32 v235, v235, v165
	v_add_f32_e32 v234, v234, v166
	ds_read_b64_tr_b16 v[230:231], v151 offset:8192
	ds_read_b64_tr_b16 v[232:233], v151 offset:10240
	s_waitcnt lgkmcnt(12)
	v_mfma_f32_32x32x16_bf16 v[16:31], v[178:181], v[238:241], v[16:31]
	v_add_f32_e32 v235, v235, v167
	v_add_f32_e32 v234, v234, v168
	v_add_f32_e32 v235, v235, v169
	v_cvt_pk_bf16_f32 v186, v162, v163
	v_cvt_pk_bf16_f32 v188, v166, v167
	ds_read_b64_tr_b16 v[238:239], v151 offset:8704
	ds_read_b64_tr_b16 v[240:241], v151 offset:10752
	s_waitcnt lgkmcnt(12)
	v_mfma_f32_32x32x16_bf16 v[0:15], v[178:181], v[242:245], v[0:15]
	v_cvt_pk_bf16_f32 v187, v164, v165
	v_cvt_pk_bf16_f32 v189, v168, v169
	v_permlane32_swap_b32_e32 v186, v188
	ds_read_b64_tr_b16 v[242:243], v151 offset:9216
	ds_read_b64_tr_b16 v[244:245], v151 offset:11264
	v_permlane32_swap_b32_e32 v187, v189
	s_waitcnt lgkmcnt(12)
	v_mfma_f32_32x32x16_bf16 v[48:63], v[182:185], v[246:249], v[48:63]
	v_exp_f32_e32 v170, v170
	v_exp_f32_e32 v171, v171
	ds_read_b64_tr_b16 v[246:247], v151 offset:9728
	ds_read_b64_tr_b16 v[248:249], v151 offset:11776
	s_waitcnt lgkmcnt(12)
	v_mfma_f32_32x32x16_bf16 v[32:47], v[182:185], v[250:253], v[32:47]
	v_exp_f32_e32 v172, v172
	v_exp_f32_e32 v173, v173
	v_add_f32_e32 v234, v234, v170
	ds_read_b64_tr_b16 v[250:251], v151 offset:12288
	ds_read_b64_tr_b16 v[252:253], v151 offset:14336
	s_waitcnt lgkmcnt(12)
	v_mfma_f32_32x32x16_bf16 v[16:31], v[182:185], v[152:155], v[16:31]
	v_exp_f32_e32 v174, v174
	v_exp_f32_e32 v175, v175
	v_add_f32_e32 v235, v235, v171
	v_add_f32_e32 v234, v234, v172
	ds_read_b64_tr_b16 v[152:153], v151 offset:12800
	ds_read_b64_tr_b16 v[154:155], v151 offset:14848
	s_waitcnt lgkmcnt(12)
	v_mfma_f32_32x32x16_bf16 v[0:15], v[182:185], v[226:229], v[0:15]
	v_exp_f32_e32 v176, v176
	v_exp_f32_e32 v177, v177
	v_add_f32_e32 v235, v235, v173
	v_add_f32_e32 v234, v234, v174
	ds_read_b64_tr_b16 v[226:227], v151 offset:13312
	ds_read_b64_tr_b16 v[228:229], v151 offset:15360
	s_waitcnt lgkmcnt(12)
	v_mfma_f32_32x32x16_bf16 v[48:63], v[186:189], v[230:233], v[48:63]
	v_add_f32_e32 v235, v235, v175
	v_add_f32_e32 v234, v234, v176
	v_add_f32_e32 v235, v235, v177
	v_cvt_pk_bf16_f32 v190, v170, v171
	v_cvt_pk_bf16_f32 v192, v174, v175
	ds_read_b64_tr_b16 v[230:231], v151 offset:13824
	ds_read_b64_tr_b16 v[232:233], v151 offset:15872
	s_waitcnt lgkmcnt(12)
	v_mfma_f32_32x32x16_bf16 v[32:47], v[186:189], v[238:241], v[32:47]
	s_add_i32 s62, s62, 0x4000
	s_cmp_ge_u32 s62, 0x14000
	s_cselect_b32 s69, 0x14000, 0
	s_sub_i32 s62, s62, s69
	v_add_u32_e32 v151, s62, v140
	v_cvt_pk_bf16_f32 v191, v172, v173
	v_cvt_pk_bf16_f32 v193, v176, v177
	v_permlane32_swap_b32_e32 v190, v192
	s_nop 0
	v_permlane32_swap_b32_e32 v191, v193
	s_waitcnt lgkmcnt(10)
	v_mfma_f32_32x32x16_bf16 v[16:31], v[186:189], v[242:245], v[16:31]
	v_exp_f32_e32 v64, v64
	v_exp_f32_e32 v65, v65
	ds_read_b128 v[194:197], v149 offset:49152
	s_waitcnt lgkmcnt(9)
	v_mfma_f32_32x32x16_bf16 v[0:15], v[186:189], v[246:249], v[0:15]
	v_exp_f32_e32 v66, v66
	v_exp_f32_e32 v67, v67
	v_add_f32_e32 v234, v234, v64
	ds_read_b128 v[198:201], v148 offset:49152
	s_waitcnt lgkmcnt(8)
	v_mfma_f32_32x32x16_bf16 v[48:63], v[190:193], v[250:253], v[48:63]
	v_exp_f32_e32 v68, v68
	v_exp_f32_e32 v69, v69
	v_add_f32_e32 v235, v235, v65
	v_add_f32_e32 v234, v234, v66
	ds_read_b128 v[202:205], v143 offset:49152
	s_waitcnt lgkmcnt(7)
	v_mfma_f32_32x32x16_bf16 v[32:47], v[190:193], v[152:155], v[32:47]
	v_exp_f32_e32 v70, v70
	v_exp_f32_e32 v71, v71
	v_add_f32_e32 v235, v235, v67
	v_add_f32_e32 v234, v234, v68
	ds_read_b128 v[206:209], v141 offset:49152
	s_waitcnt lgkmcnt(6)
	v_mfma_f32_32x32x16_bf16 v[16:31], v[190:193], v[226:229], v[16:31]
	v_add_f32_e32 v235, v235, v69
	v_add_f32_e32 v234, v234, v70
	v_add_f32_e32 v235, v235, v71
	v_cvt_pk_bf16_f32 v178, v64, v65
	v_cvt_pk_bf16_f32 v180, v68, v69
	ds_read_b128 v[210:213], v149 offset:57344
	s_waitcnt lgkmcnt(5)
	v_mfma_f32_32x32x16_bf16 v[0:15], v[190:193], v[230:233], v[0:15]
	v_cvt_pk_bf16_f32 v179, v66, v67
	v_cvt_pk_bf16_f32 v181, v70, v71
	v_permlane32_swap_b32_e32 v178, v180
	ds_read_b128 v[214:217], v148 offset:57344
	v_permlane32_swap_b32_e32 v179, v181
	s_waitcnt lgkmcnt(5)
	v_mfma_f32_32x32x16_bf16 v[96:111], v[194:197], v[124:127], 0
	v_exp_f32_e32 v72, v72
	v_exp_f32_e32 v73, v73
	ds_read_b128 v[218:221], v143 offset:57344
	s_waitcnt lgkmcnt(5)
	v_mfma_f32_32x32x16_bf16 v[96:111], v[198:201], v[120:123], v[96:111]
	v_exp_f32_e32 v74, v74
	v_exp_f32_e32 v75, v75
	v_add_f32_e32 v234, v234, v72
	ds_read_b128 v[222:225], v141 offset:57344
	ds_read_b64_tr_b16 v[226:227], v151 offset:0
	ds_read_b64_tr_b16 v[228:229], v151 offset:2048
	s_waitcnt lgkmcnt(7)
	v_mfma_f32_32x32x16_bf16 v[96:111], v[202:205], v[116:119], v[96:111]
	v_exp_f32_e32 v76, v76
	v_exp_f32_e32 v77, v77
	v_add_f32_e32 v235, v235, v73
	v_add_f32_e32 v234, v234, v74
	ds_read_b64_tr_b16 v[230:231], v151 offset:512
	ds_read_b64_tr_b16 v[232:233], v151 offset:2560
	s_waitcnt lgkmcnt(8)
	v_mfma_f32_32x32x16_bf16 v[96:111], v[206:209], v[112:115], v[96:111]
	v_exp_f32_e32 v78, v78
	v_exp_f32_e32 v79, v79
	v_add_f32_e32 v235, v235, v75
	v_add_f32_e32 v234, v234, v76
	ds_read_b64_tr_b16 v[238:239], v151 offset:1024
	ds_read_b64_tr_b16 v[240:241], v151 offset:3072
	s_waitcnt lgkmcnt(9)
	v_mfma_f32_32x32x16_bf16 v[162:177], v[210:213], v[124:127], 0
	v_add_f32_e32 v235, v235, v77
	v_add_f32_e32 v234, v234, v78
	v_add_f32_e32 v235, v235, v79
	v_cvt_pk_bf16_f32 v182, v72, v73
	v_cvt_pk_bf16_f32 v184, v76, v77
	ds_read_b64_tr_b16 v[242:243], v151 offset:1536
	ds_read_b64_tr_b16 v[244:245], v151 offset:3584
	s_waitcnt lgkmcnt(10)
	v_mfma_f32_32x32x16_bf16 v[162:177], v[214:217], v[120:123], v[162:177]
	v_cvt_pk_bf16_f32 v183, v74, v75
	v_cvt_pk_bf16_f32 v185, v78, v79
	v_permlane32_swap_b32_e32 v182, v184
	ds_read_b64_tr_b16 v[246:247], v151 offset:4096
	ds_read_b64_tr_b16 v[248:249], v151 offset:6144
	v_permlane32_swap_b32_e32 v183, v185
	s_waitcnt lgkmcnt(11)
	v_mfma_f32_32x32x16_bf16 v[162:177], v[218:221], v[116:119], v[162:177]
	v_exp_f32_e32 v80, v80
	v_exp_f32_e32 v81, v81
	ds_read_b64_tr_b16 v[250:251], v151 offset:4608
	ds_read_b64_tr_b16 v[252:253], v151 offset:6656
	s_waitcnt lgkmcnt(12)
	v_mfma_f32_32x32x16_bf16 v[162:177], v[222:225], v[112:115], v[162:177]
	v_exp_f32_e32 v82, v82
	v_exp_f32_e32 v83, v83
	v_add_f32_e32 v234, v234, v80
	ds_read_b64_tr_b16 v[152:153], v151 offset:5120
	ds_read_b64_tr_b16 v[154:155], v151 offset:7168
	s_waitcnt lgkmcnt(12)
	v_mfma_f32_32x32x16_bf16 v[48:63], v[178:181], v[226:229], v[48:63]
	v_exp_f32_e32 v84, v84
	v_exp_f32_e32 v85, v85
	v_add_f32_e32 v235, v235, v81
	v_add_f32_e32 v234, v234, v82
	ds_read_b64_tr_b16 v[226:227], v151 offset:5632
	ds_read_b64_tr_b16 v[228:229], v151 offset:7680
	s_waitcnt lgkmcnt(12)
	v_mfma_f32_32x32x16_bf16 v[32:47], v[178:181], v[230:233], v[32:47]
	v_exp_f32_e32 v86, v86
	v_exp_f32_e32 v87, v87
	v_add_f32_e32 v235, v235, v83
	v_add_f32_e32 v234, v234, v84
	ds_read_b64_tr_b16 v[230:231], v151 offset:8192
	ds_read_b64_tr_b16 v[232:233], v151 offset:10240
	s_waitcnt lgkmcnt(12)
	v_mfma_f32_32x32x16_bf16 v[16:31], v[178:181], v[238:241], v[16:31]
	v_add_f32_e32 v235, v235, v85
	v_add_f32_e32 v234, v234, v86
	v_add_f32_e32 v235, v235, v87
	v_cvt_pk_bf16_f32 v186, v80, v81
	v_cvt_pk_bf16_f32 v188, v84, v85
	ds_read_b64_tr_b16 v[238:239], v151 offset:8704
	ds_read_b64_tr_b16 v[240:241], v151 offset:10752
	s_waitcnt lgkmcnt(12)
	v_mfma_f32_32x32x16_bf16 v[0:15], v[178:181], v[242:245], v[0:15]
	v_cvt_pk_bf16_f32 v187, v82, v83
	v_cvt_pk_bf16_f32 v189, v86, v87
	v_permlane32_swap_b32_e32 v186, v188
	ds_read_b64_tr_b16 v[242:243], v151 offset:9216
	ds_read_b64_tr_b16 v[244:245], v151 offset:11264
	v_permlane32_swap_b32_e32 v187, v189
	s_waitcnt lgkmcnt(12)
	v_mfma_f32_32x32x16_bf16 v[48:63], v[182:185], v[246:249], v[48:63]
	v_exp_f32_e32 v88, v88
	v_exp_f32_e32 v89, v89
	ds_read_b64_tr_b16 v[246:247], v151 offset:9728
	ds_read_b64_tr_b16 v[248:249], v151 offset:11776
	s_waitcnt lgkmcnt(12)
	v_mfma_f32_32x32x16_bf16 v[32:47], v[182:185], v[250:253], v[32:47]
	v_exp_f32_e32 v90, v90
	v_exp_f32_e32 v91, v91
	v_add_f32_e32 v234, v234, v88
	ds_read_b64_tr_b16 v[250:251], v151 offset:12288
	ds_read_b64_tr_b16 v[252:253], v151 offset:14336
	s_waitcnt lgkmcnt(12)
	v_mfma_f32_32x32x16_bf16 v[16:31], v[182:185], v[152:155], v[16:31]
	v_exp_f32_e32 v92, v92
	v_exp_f32_e32 v93, v93
	v_add_f32_e32 v235, v235, v89
	v_add_f32_e32 v234, v234, v90
	ds_read_b64_tr_b16 v[152:153], v151 offset:12800
	ds_read_b64_tr_b16 v[154:155], v151 offset:14848
	s_waitcnt lgkmcnt(12)
	v_mfma_f32_32x32x16_bf16 v[0:15], v[182:185], v[226:229], v[0:15]
	v_exp_f32_e32 v94, v94
	v_exp_f32_e32 v95, v95
	v_add_f32_e32 v235, v235, v91
	v_add_f32_e32 v234, v234, v92
	ds_read_b64_tr_b16 v[226:227], v151 offset:13312
	ds_read_b64_tr_b16 v[228:229], v151 offset:15360
	s_waitcnt lgkmcnt(12)
	v_mfma_f32_32x32x16_bf16 v[48:63], v[186:189], v[230:233], v[48:63]
	v_add_f32_e32 v235, v235, v93
	v_add_f32_e32 v234, v234, v94
	v_add_f32_e32 v235, v235, v95
	v_cvt_pk_bf16_f32 v190, v88, v89
	v_cvt_pk_bf16_f32 v192, v92, v93
	ds_read_b64_tr_b16 v[230:231], v151 offset:13824
	ds_read_b64_tr_b16 v[232:233], v151 offset:15872
	s_waitcnt lgkmcnt(12)
	v_mfma_f32_32x32x16_bf16 v[32:47], v[186:189], v[238:241], v[32:47]
	s_waitcnt vmcnt(0)
	s_barrier
	s_add_i32 s63, s62, 0xc000
	s_cmp_ge_u32 s63, 0x14000
	s_cselect_b32 s69, 0x14000, 0
	s_sub_i32 s63, s63, s69
	s_add_i32 s68, s62, 0x10000
	s_cmp_ge_u32 s68, 0x14000
	s_cselect_b32 s69, 0x14000, 0
	s_sub_i32 s68, s68, s69
	s_add_i32 s62, s62, 0x4000
	s_cmp_ge_u32 s62, 0x14000
	s_cselect_b32 s69, 0x14000, 0
	s_sub_i32 s62, s62, s69
	v_add_u32_e32 v151, s62, v140
	v_cvt_pk_bf16_f32 v191, v90, v91
	v_cvt_pk_bf16_f32 v193, v94, v95
	v_permlane32_swap_b32_e32 v190, v192
	s_nop 0
	v_permlane32_swap_b32_e32 v191, v193
	s_add_i32 m0, s41, s63
	v_lshl_add_u64 v[146:147], v[132:133], 0, s[42:43]
	global_load_lds_dwordx4 v[146:147], off
	s_waitcnt lgkmcnt(10)
	v_mfma_f32_32x32x16_bf16 v[16:31], v[186:189], v[242:245], v[16:31]
	v_exp_f32_e32 v96, v96
	v_exp_f32_e32 v97, v97
	ds_read_b128 v[194:197], v149 offset:0
	s_add_i32 m0, s71, s63
	v_lshl_add_u64 v[254:255], v[132:133], 0, s[46:47]
	global_load_lds_dwordx4 v[254:255], off
	s_waitcnt lgkmcnt(9)
	v_mfma_f32_32x32x16_bf16 v[0:15], v[186:189], v[246:249], v[0:15]
	v_exp_f32_e32 v98, v98
	v_exp_f32_e32 v99, v99
	v_add_f32_e32 v234, v234, v96
	ds_read_b128 v[198:201], v148 offset:0
	s_add_i32 m0, s40, 0x8000
	v_lshl_add_u64 v[146:147], v[134:135], 0, s[84:85]
	global_load_lds_dwordx4 v[146:147], off
	s_waitcnt lgkmcnt(8)
	v_mfma_f32_32x32x16_bf16 v[48:63], v[190:193], v[250:253], v[48:63]
	v_exp_f32_e32 v100, v100
	v_exp_f32_e32 v101, v101
	v_add_f32_e32 v235, v235, v97
	v_add_f32_e32 v234, v234, v98
	ds_read_b128 v[202:205], v143 offset:0
	s_add_i32 m0, s40, 0xa000
	v_lshl_add_u64 v[254:255], v[134:135], 0, s[86:87]
	global_load_lds_dwordx4 v[254:255], off
	s_waitcnt lgkmcnt(7)
	v_mfma_f32_32x32x16_bf16 v[32:47], v[190:193], v[152:155], v[32:47]
	v_exp_f32_e32 v102, v102
	v_exp_f32_e32 v103, v103
	v_add_f32_e32 v235, v235, v99
	v_add_f32_e32 v234, v234, v100
	ds_read_b128 v[206:209], v141 offset:0
	s_add_i32 m0, s41, s68
	v_lshl_add_u64 v[146:147], v[132:133], 0, s[88:89]
	global_load_lds_dwordx4 v[146:147], off
	s_waitcnt lgkmcnt(6)
	v_mfma_f32_32x32x16_bf16 v[16:31], v[190:193], v[226:229], v[16:31]
	v_add_f32_e32 v235, v235, v101
	v_add_f32_e32 v234, v234, v102
	v_add_f32_e32 v235, v235, v103
	v_cvt_pk_bf16_f32 v178, v96, v97
	v_cvt_pk_bf16_f32 v180, v100, v101
	ds_read_b128 v[210:213], v149 offset:8192
	s_add_i32 m0, s71, s68
	v_lshl_add_u64 v[254:255], v[132:133], 0, s[90:91]
	global_load_lds_dwordx4 v[254:255], off
	s_waitcnt lgkmcnt(5)
	v_mfma_f32_32x32x16_bf16 v[0:15], v[190:193], v[230:233], v[0:15]
	v_cvt_pk_bf16_f32 v179, v98, v99
	v_cvt_pk_bf16_f32 v181, v102, v103
	v_permlane32_swap_b32_e32 v178, v180
	ds_read_b128 v[214:217], v148 offset:8192
	v_permlane32_swap_b32_e32 v179, v181
	s_add_i32 m0, s40, 0xc000
	v_lshl_add_u64 v[146:147], v[134:135], 0, s[92:93]
	global_load_lds_dwordx4 v[146:147], off
	s_add_i32 m0, s40, 0xe000
	v_lshl_add_u64 v[254:255], v[134:135], 0, s[94:95]
	global_load_lds_dwordx4 v[254:255], off
	v_lshl_add_u64 v[132:133], v[132:133], 0, s[12:13]
	v_lshl_add_u64 v[134:135], v[134:135], 0, s[12:13]
	s_waitcnt lgkmcnt(5)
	v_mfma_f32_32x32x16_bf16 v[64:79], v[194:197], v[124:127], 0
	v_exp_f32_e32 v104, v104
	v_exp_f32_e32 v105, v105
	ds_read_b128 v[218:221], v143 offset:8192
	s_waitcnt lgkmcnt(5)
	v_mfma_f32_32x32x16_bf16 v[64:79], v[198:201], v[120:123], v[64:79]
	v_exp_f32_e32 v106, v106
	v_exp_f32_e32 v107, v107
	v_add_f32_e32 v234, v234, v104
	ds_read_b128 v[222:225], v141 offset:8192
	ds_read_b64_tr_b16 v[226:227], v151 offset:0
	ds_read_b64_tr_b16 v[228:229], v151 offset:2048
	s_waitcnt lgkmcnt(7)
	v_mfma_f32_32x32x16_bf16 v[64:79], v[202:205], v[116:119], v[64:79]
	v_exp_f32_e32 v108, v108
	v_exp_f32_e32 v109, v109
	v_add_f32_e32 v235, v235, v105
	v_add_f32_e32 v234, v234, v106
	ds_read_b64_tr_b16 v[230:231], v151 offset:512
	ds_read_b64_tr_b16 v[232:233], v151 offset:2560
	s_waitcnt lgkmcnt(8)
	v_mfma_f32_32x32x16_bf16 v[64:79], v[206:209], v[112:115], v[64:79]
	v_exp_f32_e32 v110, v110
	v_exp_f32_e32 v111, v111
	v_add_f32_e32 v235, v235, v107
	v_add_f32_e32 v234, v234, v108
	ds_read_b64_tr_b16 v[238:239], v151 offset:1024
	ds_read_b64_tr_b16 v[240:241], v151 offset:3072
	s_waitcnt lgkmcnt(9)
	v_mfma_f32_32x32x16_bf16 v[80:95], v[210:213], v[124:127], 0
	v_add_f32_e32 v235, v235, v109
	v_add_f32_e32 v234, v234, v110
	v_add_f32_e32 v235, v235, v111
	v_cvt_pk_bf16_f32 v182, v104, v105
	v_cvt_pk_bf16_f32 v184, v108, v109
	ds_read_b64_tr_b16 v[242:243], v151 offset:1536
	ds_read_b64_tr_b16 v[244:245], v151 offset:3584
	s_waitcnt lgkmcnt(10)
	v_mfma_f32_32x32x16_bf16 v[80:95], v[214:217], v[120:123], v[80:95]
	v_cvt_pk_bf16_f32 v183, v106, v107
	v_cvt_pk_bf16_f32 v185, v110, v111
	v_permlane32_swap_b32_e32 v182, v184
	ds_read_b64_tr_b16 v[246:247], v151 offset:4096
	ds_read_b64_tr_b16 v[248:249], v151 offset:6144
	v_permlane32_swap_b32_e32 v183, v185
	s_waitcnt lgkmcnt(11)
	v_mfma_f32_32x32x16_bf16 v[80:95], v[218:221], v[116:119], v[80:95]
	v_exp_f32_e32 v162, v162
	v_exp_f32_e32 v163, v163
	ds_read_b64_tr_b16 v[250:251], v151 offset:4608
	ds_read_b64_tr_b16 v[252:253], v151 offset:6656
	s_waitcnt lgkmcnt(12)
	v_mfma_f32_32x32x16_bf16 v[80:95], v[222:225], v[112:115], v[80:95]
	v_exp_f32_e32 v164, v164
	v_exp_f32_e32 v165, v165
	v_add_f32_e32 v234, v234, v162
	ds_read_b64_tr_b16 v[152:153], v151 offset:5120
	ds_read_b64_tr_b16 v[154:155], v151 offset:7168
	s_waitcnt lgkmcnt(12)
	v_mfma_f32_32x32x16_bf16 v[48:63], v[178:181], v[226:229], v[48:63]
	v_exp_f32_e32 v166, v166
	v_exp_f32_e32 v167, v167
	v_add_f32_e32 v235, v235, v163
	v_add_f32_e32 v234, v234, v164
	ds_read_b64_tr_b16 v[226:227], v151 offset:5632
	ds_read_b64_tr_b16 v[228:229], v151 offset:7680
	s_waitcnt lgkmcnt(12)
	v_mfma_f32_32x32x16_bf16 v[32:47], v[178:181], v[230:233], v[32:47]
	v_exp_f32_e32 v168, v168
	v_exp_f32_e32 v169, v169
	v_add_f32_e32 v235, v235, v165
	v_add_f32_e32 v234, v234, v166
	ds_read_b64_tr_b16 v[230:231], v151 offset:8192
	ds_read_b64_tr_b16 v[232:233], v151 offset:10240
	s_waitcnt lgkmcnt(12)
	v_mfma_f32_32x32x16_bf16 v[16:31], v[178:181], v[238:241], v[16:31]
	v_add_f32_e32 v235, v235, v167
	v_add_f32_e32 v234, v234, v168
	v_add_f32_e32 v235, v235, v169
	v_cvt_pk_bf16_f32 v186, v162, v163
	v_cvt_pk_bf16_f32 v188, v166, v167
	ds_read_b64_tr_b16 v[238:239], v151 offset:8704
	ds_read_b64_tr_b16 v[240:241], v151 offset:10752
	s_waitcnt lgkmcnt(12)
	v_mfma_f32_32x32x16_bf16 v[0:15], v[178:181], v[242:245], v[0:15]
	v_cvt_pk_bf16_f32 v187, v164, v165
	v_cvt_pk_bf16_f32 v189, v168, v169
	v_permlane32_swap_b32_e32 v186, v188
	ds_read_b64_tr_b16 v[242:243], v151 offset:9216
	ds_read_b64_tr_b16 v[244:245], v151 offset:11264
	v_permlane32_swap_b32_e32 v187, v189
	s_waitcnt lgkmcnt(12)
	v_mfma_f32_32x32x16_bf16 v[48:63], v[182:185], v[246:249], v[48:63]
	v_exp_f32_e32 v170, v170
	v_exp_f32_e32 v171, v171
	ds_read_b64_tr_b16 v[246:247], v151 offset:9728
	ds_read_b64_tr_b16 v[248:249], v151 offset:11776
	s_waitcnt lgkmcnt(12)
	v_mfma_f32_32x32x16_bf16 v[32:47], v[182:185], v[250:253], v[32:47]
	v_exp_f32_e32 v172, v172
	v_exp_f32_e32 v173, v173
	v_add_f32_e32 v234, v234, v170
	ds_read_b64_tr_b16 v[250:251], v151 offset:12288
	ds_read_b64_tr_b16 v[252:253], v151 offset:14336
	s_waitcnt lgkmcnt(12)
	v_mfma_f32_32x32x16_bf16 v[16:31], v[182:185], v[152:155], v[16:31]
	v_exp_f32_e32 v174, v174
	v_exp_f32_e32 v175, v175
	v_add_f32_e32 v235, v235, v171
	v_add_f32_e32 v234, v234, v172
	ds_read_b64_tr_b16 v[152:153], v151 offset:12800
	ds_read_b64_tr_b16 v[154:155], v151 offset:14848
	s_waitcnt lgkmcnt(12)
	v_mfma_f32_32x32x16_bf16 v[0:15], v[182:185], v[226:229], v[0:15]
	v_exp_f32_e32 v176, v176
	v_exp_f32_e32 v177, v177
	v_add_f32_e32 v235, v235, v173
	v_add_f32_e32 v234, v234, v174
	ds_read_b64_tr_b16 v[226:227], v151 offset:13312
	ds_read_b64_tr_b16 v[228:229], v151 offset:15360
	s_waitcnt lgkmcnt(12)
	v_mfma_f32_32x32x16_bf16 v[48:63], v[186:189], v[230:233], v[48:63]
	v_add_f32_e32 v235, v235, v175
	v_add_f32_e32 v234, v234, v176
	v_add_f32_e32 v235, v235, v177
	v_cvt_pk_bf16_f32 v190, v170, v171
	v_cvt_pk_bf16_f32 v192, v174, v175
	ds_read_b64_tr_b16 v[230:231], v151 offset:13824
	ds_read_b64_tr_b16 v[232:233], v151 offset:15872
	s_waitcnt lgkmcnt(12)
	v_mfma_f32_32x32x16_bf16 v[32:47], v[186:189], v[238:241], v[32:47]
	s_add_i32 s62, s62, 0x4000
	s_cmp_ge_u32 s62, 0x14000
	s_cselect_b32 s69, 0x14000, 0
	s_sub_i32 s62, s62, s69
	v_add_u32_e32 v151, s62, v140
	v_cvt_pk_bf16_f32 v191, v172, v173
	v_cvt_pk_bf16_f32 v193, v176, v177
	v_permlane32_swap_b32_e32 v190, v192
	s_nop 0
	v_permlane32_swap_b32_e32 v191, v193
	s_waitcnt lgkmcnt(10)
	v_mfma_f32_32x32x16_bf16 v[16:31], v[186:189], v[242:245], v[16:31]
	v_exp_f32_e32 v64, v64
	v_exp_f32_e32 v65, v65
	ds_read_b128 v[194:197], v149 offset:16384
	s_waitcnt lgkmcnt(9)
	v_mfma_f32_32x32x16_bf16 v[0:15], v[186:189], v[246:249], v[0:15]
	v_exp_f32_e32 v66, v66
	v_exp_f32_e32 v67, v67
	v_add_f32_e32 v234, v234, v64
	ds_read_b128 v[198:201], v148 offset:16384
	s_waitcnt lgkmcnt(8)
	v_mfma_f32_32x32x16_bf16 v[48:63], v[190:193], v[250:253], v[48:63]
	v_exp_f32_e32 v68, v68
	v_exp_f32_e32 v69, v69
	v_add_f32_e32 v235, v235, v65
	v_add_f32_e32 v234, v234, v66
	ds_read_b128 v[202:205], v143 offset:16384
	s_waitcnt lgkmcnt(7)
	v_mfma_f32_32x32x16_bf16 v[32:47], v[190:193], v[152:155], v[32:47]
	v_exp_f32_e32 v70, v70
	v_exp_f32_e32 v71, v71
	v_add_f32_e32 v235, v235, v67
	v_add_f32_e32 v234, v234, v68
	ds_read_b128 v[206:209], v141 offset:16384
	s_waitcnt lgkmcnt(6)
	v_mfma_f32_32x32x16_bf16 v[16:31], v[190:193], v[226:229], v[16:31]
	v_add_f32_e32 v235, v235, v69
	v_add_f32_e32 v234, v234, v70
	v_add_f32_e32 v235, v235, v71
	v_cvt_pk_bf16_f32 v178, v64, v65
	v_cvt_pk_bf16_f32 v180, v68, v69
	ds_read_b128 v[210:213], v149 offset:24576
	s_waitcnt lgkmcnt(5)
	v_mfma_f32_32x32x16_bf16 v[0:15], v[190:193], v[230:233], v[0:15]
	v_cvt_pk_bf16_f32 v179, v66, v67
	v_cvt_pk_bf16_f32 v181, v70, v71
	v_permlane32_swap_b32_e32 v178, v180
	ds_read_b128 v[214:217], v148 offset:24576
	v_permlane32_swap_b32_e32 v179, v181
	s_sub_i32 s70, s70, 1
	s_cmp_lg_u32 s70, 0
	s_cbranch_scc1 .Lda_loop
	s_waitcnt lgkmcnt(5)
	v_mfma_f32_32x32x16_bf16 v[96:111], v[194:197], v[124:127], 0
	v_exp_f32_e32 v72, v72
	v_exp_f32_e32 v73, v73
	ds_read_b128 v[218:221], v143 offset:24576
	s_waitcnt lgkmcnt(5)
	v_mfma_f32_32x32x16_bf16 v[96:111], v[198:201], v[120:123], v[96:111]
	v_exp_f32_e32 v74, v74
	v_exp_f32_e32 v75, v75
	v_add_f32_e32 v234, v234, v72
	ds_read_b128 v[222:225], v141 offset:24576
	ds_read_b64_tr_b16 v[226:227], v151 offset:0
	ds_read_b64_tr_b16 v[228:229], v151 offset:2048
	s_waitcnt lgkmcnt(7)
	v_mfma_f32_32x32x16_bf16 v[96:111], v[202:205], v[116:119], v[96:111]
	v_exp_f32_e32 v76, v76
	v_exp_f32_e32 v77, v77
	v_add_f32_e32 v235, v235, v73
	v_add_f32_e32 v234, v234, v74
	ds_read_b64_tr_b16 v[230:231], v151 offset:512
	ds_read_b64_tr_b16 v[232:233], v151 offset:2560
	s_waitcnt lgkmcnt(8)
	v_mfma_f32_32x32x16_bf16 v[96:111], v[206:209], v[112:115], v[96:111]
	v_exp_f32_e32 v78, v78
	v_exp_f32_e32 v79, v79
	v_add_f32_e32 v235, v235, v75
	v_add_f32_e32 v234, v234, v76
	ds_read_b64_tr_b16 v[238:239], v151 offset:1024
	ds_read_b64_tr_b16 v[240:241], v151 offset:3072
	s_waitcnt lgkmcnt(9)
	v_mfma_f32_32x32x16_bf16 v[162:177], v[210:213], v[124:127], 0
	v_add_f32_e32 v235, v235, v77
	v_add_f32_e32 v234, v234, v78
	v_add_f32_e32 v235, v235, v79
	v_cvt_pk_bf16_f32 v182, v72, v73
	v_cvt_pk_bf16_f32 v184, v76, v77
	ds_read_b64_tr_b16 v[242:243], v151 offset:1536
	ds_read_b64_tr_b16 v[244:245], v151 offset:3584
	s_waitcnt lgkmcnt(10)
	v_mfma_f32_32x32x16_bf16 v[162:177], v[214:217], v[120:123], v[162:177]
	v_cvt_pk_bf16_f32 v183, v74, v75
	v_cvt_pk_bf16_f32 v185, v78, v79
	v_permlane32_swap_b32_e32 v182, v184
	ds_read_b64_tr_b16 v[246:247], v151 offset:4096
	ds_read_b64_tr_b16 v[248:249], v151 offset:6144
	v_permlane32_swap_b32_e32 v183, v185
	s_waitcnt lgkmcnt(11)
	v_mfma_f32_32x32x16_bf16 v[162:177], v[218:221], v[116:119], v[162:177]
	v_exp_f32_e32 v80, v80
	v_exp_f32_e32 v81, v81
	ds_read_b64_tr_b16 v[250:251], v151 offset:4608
	ds_read_b64_tr_b16 v[252:253], v151 offset:6656
	s_waitcnt lgkmcnt(12)
	v_mfma_f32_32x32x16_bf16 v[162:177], v[222:225], v[112:115], v[162:177]
	v_exp_f32_e32 v82, v82
	v_exp_f32_e32 v83, v83
	v_add_f32_e32 v234, v234, v80
	ds_read_b64_tr_b16 v[152:153], v151 offset:5120
	ds_read_b64_tr_b16 v[154:155], v151 offset:7168
	s_waitcnt lgkmcnt(12)
	v_mfma_f32_32x32x16_bf16 v[48:63], v[178:181], v[226:229], v[48:63]
	v_exp_f32_e32 v84, v84
	v_exp_f32_e32 v85, v85
	v_add_f32_e32 v235, v235, v81
	v_add_f32_e32 v234, v234, v82
	ds_read_b64_tr_b16 v[226:227], v151 offset:5632
	ds_read_b64_tr_b16 v[228:229], v151 offset:7680
	s_waitcnt lgkmcnt(12)
	v_mfma_f32_32x32x16_bf16 v[32:47], v[178:181], v[230:233], v[32:47]
	v_exp_f32_e32 v86, v86
	v_exp_f32_e32 v87, v87
	v_add_f32_e32 v235, v235, v83
	v_add_f32_e32 v234, v234, v84
	ds_read_b64_tr_b16 v[230:231], v151 offset:8192
	ds_read_b64_tr_b16 v[232:233], v151 offset:10240
	s_waitcnt lgkmcnt(12)
	v_mfma_f32_32x32x16_bf16 v[16:31], v[178:181], v[238:241], v[16:31]
	v_add_f32_e32 v235, v235, v85
	v_add_f32_e32 v234, v234, v86
	v_add_f32_e32 v235, v235, v87
	v_cvt_pk_bf16_f32 v186, v80, v81
	v_cvt_pk_bf16_f32 v188, v84, v85
	ds_read_b64_tr_b16 v[238:239], v151 offset:8704
	ds_read_b64_tr_b16 v[240:241], v151 offset:10752
	s_waitcnt lgkmcnt(12)
	v_mfma_f32_32x32x16_bf16 v[0:15], v[178:181], v[242:245], v[0:15]
	v_cvt_pk_bf16_f32 v187, v82, v83
	v_cvt_pk_bf16_f32 v189, v86, v87
	v_permlane32_swap_b32_e32 v186, v188
	ds_read_b64_tr_b16 v[242:243], v151 offset:9216
	ds_read_b64_tr_b16 v[244:245], v151 offset:11264
	v_permlane32_swap_b32_e32 v187, v189
	s_waitcnt lgkmcnt(12)
	v_mfma_f32_32x32x16_bf16 v[48:63], v[182:185], v[246:249], v[48:63]
	v_exp_f32_e32 v88, v88
	v_exp_f32_e32 v89, v89
	ds_read_b64_tr_b16 v[246:247], v151 offset:9728
	ds_read_b64_tr_b16 v[248:249], v151 offset:11776
	s_waitcnt lgkmcnt(12)
	v_mfma_f32_32x32x16_bf16 v[32:47], v[182:185], v[250:253], v[32:47]
	v_exp_f32_e32 v90, v90
	v_exp_f32_e32 v91, v91
	v_add_f32_e32 v234, v234, v88
	ds_read_b64_tr_b16 v[250:251], v151 offset:12288
	ds_read_b64_tr_b16 v[252:253], v151 offset:14336
	s_waitcnt lgkmcnt(12)
	v_mfma_f32_32x32x16_bf16 v[16:31], v[182:185], v[152:155], v[16:31]
	v_exp_f32_e32 v92, v92
	v_exp_f32_e32 v93, v93
	v_add_f32_e32 v235, v235, v89
	v_add_f32_e32 v234, v234, v90
	ds_read_b64_tr_b16 v[152:153], v151 offset:12800
	ds_read_b64_tr_b16 v[154:155], v151 offset:14848
	s_waitcnt lgkmcnt(12)
	v_mfma_f32_32x32x16_bf16 v[0:15], v[182:185], v[226:229], v[0:15]
	v_exp_f32_e32 v94, v94
	v_exp_f32_e32 v95, v95
	v_add_f32_e32 v235, v235, v91
	v_add_f32_e32 v234, v234, v92
	ds_read_b64_tr_b16 v[226:227], v151 offset:13312
	ds_read_b64_tr_b16 v[228:229], v151 offset:15360
	s_waitcnt lgkmcnt(12)
	v_mfma_f32_32x32x16_bf16 v[48:63], v[186:189], v[230:233], v[48:63]
	v_add_f32_e32 v235, v235, v93
	v_add_f32_e32 v234, v234, v94
	v_add_f32_e32 v235, v235, v95
	v_cvt_pk_bf16_f32 v190, v88, v89
	v_cvt_pk_bf16_f32 v192, v92, v93
	ds_read_b64_tr_b16 v[230:231], v151 offset:13824
	ds_read_b64_tr_b16 v[232:233], v151 offset:15872
	s_waitcnt lgkmcnt(12)
	v_mfma_f32_32x32x16_bf16 v[32:47], v[186:189], v[238:241], v[32:47]
	s_waitcnt vmcnt(0)
	s_barrier
	s_add_i32 s63, s62, 0xc000
	s_cmp_ge_u32 s63, 0x14000
	s_cselect_b32 s69, 0x14000, 0
	s_sub_i32 s63, s63, s69
	s_add_i32 s62, s62, 0x4000
	s_cmp_ge_u32 s62, 0x14000
	s_cselect_b32 s69, 0x14000, 0
	s_sub_i32 s62, s62, s69
	v_add_u32_e32 v151, s62, v140
	v_cvt_pk_bf16_f32 v191, v90, v91
	v_cvt_pk_bf16_f32 v193, v94, v95
	v_permlane32_swap_b32_e32 v190, v192
	s_nop 0
	v_permlane32_swap_b32_e32 v191, v193
	s_add_i32 m0, s41, s63
	v_lshl_add_u64 v[146:147], v[132:133], 0, s[42:43]
	global_load_lds_dwordx4 v[146:147], off
	s_waitcnt lgkmcnt(10)
	v_mfma_f32_32x32x16_bf16 v[16:31], v[186:189], v[242:245], v[16:31]
	v_exp_f32_e32 v96, v96
	v_exp_f32_e32 v97, v97
	ds_read_b128 v[194:197], v149 offset:32768
	s_add_i32 m0, s71, s63
	v_lshl_add_u64 v[254:255], v[132:133], 0, s[46:47]
	global_load_lds_dwordx4 v[254:255], off
	s_waitcnt lgkmcnt(9)
	v_mfma_f32_32x32x16_bf16 v[0:15], v[186:189], v[246:249], v[0:15]
	v_exp_f32_e32 v98, v98
	v_exp_f32_e32 v99, v99
	v_add_f32_e32 v234, v234, v96
	ds_read_b128 v[198:201], v148 offset:32768
	s_waitcnt lgkmcnt(8)
	v_mfma_f32_32x32x16_bf16 v[48:63], v[190:193], v[250:253], v[48:63]
	v_exp_f32_e32 v100, v100
	v_exp_f32_e32 v101, v101
	v_add_f32_e32 v235, v235, v97
	v_add_f32_e32 v234, v234, v98
	ds_read_b128 v[202:205], v143 offset:32768
	s_waitcnt lgkmcnt(7)
	v_mfma_f32_32x32x16_bf16 v[32:47], v[190:193], v[152:155], v[32:47]
	v_exp_f32_e32 v102, v102
	v_exp_f32_e32 v103, v103
	v_add_f32_e32 v235, v235, v99
	v_add_f32_e32 v234, v234, v100
	ds_read_b128 v[206:209], v141 offset:32768
	s_waitcnt lgkmcnt(6)
	v_mfma_f32_32x32x16_bf16 v[16:31], v[190:193], v[226:229], v[16:31]
	v_add_f32_e32 v235, v235, v101
	v_add_f32_e32 v234, v234, v102
	v_add_f32_e32 v235, v235, v103
	v_cvt_pk_bf16_f32 v178, v96, v97
	v_cvt_pk_bf16_f32 v180, v100, v101
	ds_read_b128 v[210:213], v149 offset:40960
	s_waitcnt lgkmcnt(5)
	v_mfma_f32_32x32x16_bf16 v[0:15], v[190:193], v[230:233], v[0:15]
	v_cvt_pk_bf16_f32 v179, v98, v99
	v_cvt_pk_bf16_f32 v181, v102, v103
	v_permlane32_swap_b32_e32 v178, v180
	ds_read_b128 v[214:217], v148 offset:40960
	v_permlane32_swap_b32_e32 v179, v181
	s_waitcnt lgkmcnt(5)
	v_mfma_f32_32x32x16_bf16 v[64:79], v[194:197], v[124:127], 0
	v_exp_f32_e32 v104, v104
	v_exp_f32_e32 v105, v105
	ds_read_b128 v[218:221], v143 offset:40960
	s_waitcnt lgkmcnt(5)
	v_mfma_f32_32x32x16_bf16 v[64:79], v[198:201], v[120:123], v[64:79]
	v_exp_f32_e32 v106, v106
	v_exp_f32_e32 v107, v107
	v_add_f32_e32 v234, v234, v104
	ds_read_b128 v[222:225], v141 offset:40960
	ds_read_b64_tr_b16 v[226:227], v151 offset:0
	ds_read_b64_tr_b16 v[228:229], v151 offset:2048
	s_waitcnt lgkmcnt(7)
	v_mfma_f32_32x32x16_bf16 v[64:79], v[202:205], v[116:119], v[64:79]
	v_exp_f32_e32 v108, v108
	v_exp_f32_e32 v109, v109
	v_add_f32_e32 v235, v235, v105
	v_add_f32_e32 v234, v234, v106
	ds_read_b64_tr_b16 v[230:231], v151 offset:512
	ds_read_b64_tr_b16 v[232:233], v151 offset:2560
	s_waitcnt lgkmcnt(8)
	v_mfma_f32_32x32x16_bf16 v[64:79], v[206:209], v[112:115], v[64:79]
	v_exp_f32_e32 v110, v110
	v_exp_f32_e32 v111, v111
	v_add_f32_e32 v235, v235, v107
	v_add_f32_e32 v234, v234, v108
	ds_read_b64_tr_b16 v[238:239], v151 offset:1024
	ds_read_b64_tr_b16 v[240:241], v151 offset:3072
	s_waitcnt lgkmcnt(9)
	v_mfma_f32_32x32x16_bf16 v[80:95], v[210:213], v[124:127], 0
	v_add_f32_e32 v235, v235, v109
	v_add_f32_e32 v234, v234, v110
	v_add_f32_e32 v235, v235, v111
	v_cvt_pk_bf16_f32 v182, v104, v105
	v_cvt_pk_bf16_f32 v184, v108, v109
	ds_read_b64_tr_b16 v[242:243], v151 offset:1536
	ds_read_b64_tr_b16 v[244:245], v151 offset:3584
	s_waitcnt lgkmcnt(10)
	v_mfma_f32_32x32x16_bf16 v[80:95], v[214:217], v[120:123], v[80:95]
	v_cvt_pk_bf16_f32 v183, v106, v107
	v_cvt_pk_bf16_f32 v185, v110, v111
	v_permlane32_swap_b32_e32 v182, v184
	ds_read_b64_tr_b16 v[246:247], v151 offset:4096
	ds_read_b64_tr_b16 v[248:249], v151 offset:6144
	v_permlane32_swap_b32_e32 v183, v185
	s_waitcnt lgkmcnt(11)
	v_mfma_f32_32x32x16_bf16 v[80:95], v[218:221], v[116:119], v[80:95]
	v_exp_f32_e32 v162, v162
	v_exp_f32_e32 v163, v163
	ds_read_b64_tr_b16 v[250:251], v151 offset:4608
	ds_read_b64_tr_b16 v[252:253], v151 offset:6656
	s_waitcnt lgkmcnt(12)
	v_mfma_f32_32x32x16_bf16 v[80:95], v[222:225], v[112:115], v[80:95]
	v_exp_f32_e32 v164, v164
	v_exp_f32_e32 v165, v165
	v_add_f32_e32 v234, v234, v162
	ds_read_b64_tr_b16 v[152:153], v151 offset:5120
	ds_read_b64_tr_b16 v[154:155], v151 offset:7168
	s_waitcnt lgkmcnt(12)
	v_mfma_f32_32x32x16_bf16 v[48:63], v[178:181], v[226:229], v[48:63]
	v_exp_f32_e32 v166, v166
	v_exp_f32_e32 v167, v167
	v_add_f32_e32 v235, v235, v163
	v_add_f32_e32 v234, v234, v164
	ds_read_b64_tr_b16 v[226:227], v151 offset:5632
	ds_read_b64_tr_b16 v[228:229], v151 offset:7680
	s_waitcnt lgkmcnt(12)
	v_mfma_f32_32x32x16_bf16 v[32:47], v[178:181], v[230:233], v[32:47]
	v_exp_f32_e32 v168, v168
	v_exp_f32_e32 v169, v169
	v_add_f32_e32 v235, v235, v165
	v_add_f32_e32 v234, v234, v166
	ds_read_b64_tr_b16 v[230:231], v151 offset:8192
	ds_read_b64_tr_b16 v[232:233], v151 offset:10240
	s_waitcnt lgkmcnt(12)
	v_mfma_f32_32x32x16_bf16 v[16:31], v[178:181], v[238:241], v[16:31]
	v_add_f32_e32 v235, v235, v167
	v_add_f32_e32 v234, v234, v168
	v_add_f32_e32 v235, v235, v169
	v_cvt_pk_bf16_f32 v186, v162, v163
	v_cvt_pk_bf16_f32 v188, v166, v167
	ds_read_b64_tr_b16 v[238:239], v151 offset:8704
	ds_read_b64_tr_b16 v[240:241], v151 offset:10752
	s_waitcnt lgkmcnt(12)
	v_mfma_f32_32x32x16_bf16 v[0:15], v[178:181], v[242:245], v[0:15]
	v_cvt_pk_bf16_f32 v187, v164, v165
	v_cvt_pk_bf16_f32 v189, v168, v169
	v_permlane32_swap_b32_e32 v186, v188
	ds_read_b64_tr_b16 v[242:243], v151 offset:9216
	ds_read_b64_tr_b16 v[244:245], v151 offset:11264
	v_permlane32_swap_b32_e32 v187, v189
	s_waitcnt lgkmcnt(12)
	v_mfma_f32_32x32x16_bf16 v[48:63], v[182:185], v[246:249], v[48:63]
	v_exp_f32_e32 v170, v170
	v_exp_f32_e32 v171, v171
	ds_read_b64_tr_b16 v[246:247], v151 offset:9728
	ds_read_b64_tr_b16 v[248:249], v151 offset:11776
	s_waitcnt lgkmcnt(12)
	v_mfma_f32_32x32x16_bf16 v[32:47], v[182:185], v[250:253], v[32:47]
	v_exp_f32_e32 v172, v172
	v_exp_f32_e32 v173, v173
	v_add_f32_e32 v234, v234, v170
	ds_read_b64_tr_b16 v[250:251], v151 offset:12288
	ds_read_b64_tr_b16 v[252:253], v151 offset:14336
	s_waitcnt lgkmcnt(12)
	v_mfma_f32_32x32x16_bf16 v[16:31], v[182:185], v[152:155], v[16:31]
	v_exp_f32_e32 v174, v174
	v_exp_f32_e32 v175, v175
	v_add_f32_e32 v235, v235, v171
	v_add_f32_e32 v234, v234, v172
	ds_read_b64_tr_b16 v[152:153], v151 offset:12800
	ds_read_b64_tr_b16 v[154:155], v151 offset:14848
	s_waitcnt lgkmcnt(12)
	v_mfma_f32_32x32x16_bf16 v[0:15], v[182:185], v[226:229], v[0:15]
	v_exp_f32_e32 v176, v176
	v_exp_f32_e32 v177, v177
	v_add_f32_e32 v235, v235, v173
	v_add_f32_e32 v234, v234, v174
	ds_read_b64_tr_b16 v[226:227], v151 offset:13312
	ds_read_b64_tr_b16 v[228:229], v151 offset:15360
	s_waitcnt lgkmcnt(12)
	v_mfma_f32_32x32x16_bf16 v[48:63], v[186:189], v[230:233], v[48:63]
	v_add_f32_e32 v235, v235, v175
	v_add_f32_e32 v234, v234, v176
	v_add_f32_e32 v235, v235, v177
	v_cvt_pk_bf16_f32 v190, v170, v171
	v_cvt_pk_bf16_f32 v192, v174, v175
	ds_read_b64_tr_b16 v[230:231], v151 offset:13824
	ds_read_b64_tr_b16 v[232:233], v151 offset:15872
	s_waitcnt lgkmcnt(12)
	v_mfma_f32_32x32x16_bf16 v[32:47], v[186:189], v[238:241], v[32:47]
	s_add_i32 s62, s62, 0x4000
	s_cmp_ge_u32 s62, 0x14000
	s_cselect_b32 s69, 0x14000, 0
	s_sub_i32 s62, s62, s69
	v_add_u32_e32 v151, s62, v140
	v_cvt_pk_bf16_f32 v191, v172, v173
	v_cvt_pk_bf16_f32 v193, v176, v177
	v_permlane32_swap_b32_e32 v190, v192
	s_nop 0
	v_permlane32_swap_b32_e32 v191, v193
	s_waitcnt lgkmcnt(10)
	v_mfma_f32_32x32x16_bf16 v[16:31], v[186:189], v[242:245], v[16:31]
	v_exp_f32_e32 v64, v64
	v_exp_f32_e32 v65, v65
	ds_read_b128 v[194:197], v149 offset:49152
	s_waitcnt lgkmcnt(9)
	v_mfma_f32_32x32x16_bf16 v[0:15], v[186:189], v[246:249], v[0:15]
	v_exp_f32_e32 v66, v66
	v_exp_f32_e32 v67, v67
	v_add_f32_e32 v234, v234, v64
	ds_read_b128 v[198:201], v148 offset:49152
	s_waitcnt lgkmcnt(8)
	v_mfma_f32_32x32x16_bf16 v[48:63], v[190:193], v[250:253], v[48:63]
	v_exp_f32_e32 v68, v68
	v_exp_f32_e32 v69, v69
	v_add_f32_e32 v235, v235, v65
	v_add_f32_e32 v234, v234, v66
	ds_read_b128 v[202:205], v143 offset:49152
	s_waitcnt lgkmcnt(7)
	v_mfma_f32_32x32x16_bf16 v[32:47], v[190:193], v[152:155], v[32:47]
	v_exp_f32_e32 v70, v70
	v_exp_f32_e32 v71, v71
	v_add_f32_e32 v235, v235, v67
	v_add_f32_e32 v234, v234, v68
	ds_read_b128 v[206:209], v141 offset:49152
	s_waitcnt lgkmcnt(6)
	v_mfma_f32_32x32x16_bf16 v[16:31], v[190:193], v[226:229], v[16:31]
	v_add_f32_e32 v235, v235, v69
	v_add_f32_e32 v234, v234, v70
	v_add_f32_e32 v235, v235, v71
	v_cvt_pk_bf16_f32 v178, v64, v65
	v_cvt_pk_bf16_f32 v180, v68, v69
	ds_read_b128 v[210:213], v149 offset:57344
	s_waitcnt lgkmcnt(5)
	v_mfma_f32_32x32x16_bf16 v[0:15], v[190:193], v[230:233], v[0:15]
	v_cvt_pk_bf16_f32 v179, v66, v67
	v_cvt_pk_bf16_f32 v181, v70, v71
	v_permlane32_swap_b32_e32 v178, v180
	ds_read_b128 v[214:217], v148 offset:57344
	v_permlane32_swap_b32_e32 v179, v181
	s_waitcnt lgkmcnt(5)
	v_mfma_f32_32x32x16_bf16 v[96:111], v[194:197], v[124:127], 0
	v_exp_f32_e32 v72, v72
	v_exp_f32_e32 v73, v73
	ds_read_b128 v[218:221], v143 offset:57344
	s_waitcnt lgkmcnt(5)
	v_mfma_f32_32x32x16_bf16 v[96:111], v[198:201], v[120:123], v[96:111]
	v_exp_f32_e32 v74, v74
	v_exp_f32_e32 v75, v75
	v_add_f32_e32 v234, v234, v72
	ds_read_b128 v[222:225], v141 offset:57344
	ds_read_b64_tr_b16 v[226:227], v151 offset:0
	ds_read_b64_tr_b16 v[228:229], v151 offset:2048
	s_waitcnt lgkmcnt(7)
	v_mfma_f32_32x32x16_bf16 v[96:111], v[202:205], v[116:119], v[96:111]
	v_exp_f32_e32 v76, v76
	v_exp_f32_e32 v77, v77
	v_add_f32_e32 v235, v235, v73
	v_add_f32_e32 v234, v234, v74
	ds_read_b64_tr_b16 v[230:231], v151 offset:512
	ds_read_b64_tr_b16 v[232:233], v151 offset:2560
	s_waitcnt lgkmcnt(8)
	v_mfma_f32_32x32x16_bf16 v[96:111], v[206:209], v[112:115], v[96:111]
	v_exp_f32_e32 v78, v78
	v_exp_f32_e32 v79, v79
	v_add_f32_e32 v235, v235, v75
	v_add_f32_e32 v234, v234, v76
	ds_read_b64_tr_b16 v[238:239], v151 offset:1024
	ds_read_b64_tr_b16 v[240:241], v151 offset:3072
	s_waitcnt lgkmcnt(9)
	v_mfma_f32_32x32x16_bf16 v[162:177], v[210:213], v[124:127], 0
	v_add_f32_e32 v235, v235, v77
	v_add_f32_e32 v234, v234, v78
	v_add_f32_e32 v235, v235, v79
	v_cvt_pk_bf16_f32 v182, v72, v73
	v_cvt_pk_bf16_f32 v184, v76, v77
	ds_read_b64_tr_b16 v[242:243], v151 offset:1536
	ds_read_b64_tr_b16 v[244:245], v151 offset:3584
	s_waitcnt lgkmcnt(10)
	v_mfma_f32_32x32x16_bf16 v[162:177], v[214:217], v[120:123], v[162:177]
	v_cvt_pk_bf16_f32 v183, v74, v75
	v_cvt_pk_bf16_f32 v185, v78, v79
	v_permlane32_swap_b32_e32 v182, v184
	ds_read_b64_tr_b16 v[246:247], v151 offset:4096
	ds_read_b64_tr_b16 v[248:249], v151 offset:6144
	v_permlane32_swap_b32_e32 v183, v185
	s_waitcnt lgkmcnt(11)
	v_mfma_f32_32x32x16_bf16 v[162:177], v[218:221], v[116:119], v[162:177]
	v_exp_f32_e32 v80, v80
	v_exp_f32_e32 v81, v81
	ds_read_b64_tr_b16 v[250:251], v151 offset:4608
	ds_read_b64_tr_b16 v[252:253], v151 offset:6656
	s_waitcnt lgkmcnt(12)
	v_mfma_f32_32x32x16_bf16 v[162:177], v[222:225], v[112:115], v[162:177]
	v_exp_f32_e32 v82, v82
	v_exp_f32_e32 v83, v83
	v_add_f32_e32 v234, v234, v80
	ds_read_b64_tr_b16 v[152:153], v151 offset:5120
	ds_read_b64_tr_b16 v[154:155], v151 offset:7168
	s_waitcnt lgkmcnt(12)
	v_mfma_f32_32x32x16_bf16 v[48:63], v[178:181], v[226:229], v[48:63]
	v_exp_f32_e32 v84, v84
	v_exp_f32_e32 v85, v85
	v_add_f32_e32 v235, v235, v81
	v_add_f32_e32 v234, v234, v82
	ds_read_b64_tr_b16 v[226:227], v151 offset:5632
	ds_read_b64_tr_b16 v[228:229], v151 offset:7680
	s_waitcnt lgkmcnt(12)
	v_mfma_f32_32x32x16_bf16 v[32:47], v[178:181], v[230:233], v[32:47]
	v_exp_f32_e32 v86, v86
	v_exp_f32_e32 v87, v87
	v_add_f32_e32 v235, v235, v83
	v_add_f32_e32 v234, v234, v84
	ds_read_b64_tr_b16 v[230:231], v151 offset:8192
	ds_read_b64_tr_b16 v[232:233], v151 offset:10240
	s_waitcnt lgkmcnt(12)
	v_mfma_f32_32x32x16_bf16 v[16:31], v[178:181], v[238:241], v[16:31]
	v_add_f32_e32 v235, v235, v85
	v_add_f32_e32 v234, v234, v86
	v_add_f32_e32 v235, v235, v87
	v_cvt_pk_bf16_f32 v186, v80, v81
	v_cvt_pk_bf16_f32 v188, v84, v85
	ds_read_b64_tr_b16 v[238:239], v151 offset:8704
	ds_read_b64_tr_b16 v[240:241], v151 offset:10752
	s_waitcnt lgkmcnt(12)
	v_mfma_f32_32x32x16_bf16 v[0:15], v[178:181], v[242:245], v[0:15]
	v_cvt_pk_bf16_f32 v187, v82, v83
	v_cvt_pk_bf16_f32 v189, v86, v87
	v_permlane32_swap_b32_e32 v186, v188
	ds_read_b64_tr_b16 v[242:243], v151 offset:9216
	ds_read_b64_tr_b16 v[244:245], v151 offset:11264
	v_permlane32_swap_b32_e32 v187, v189
	s_waitcnt lgkmcnt(12)
	v_mfma_f32_32x32x16_bf16 v[48:63], v[182:185], v[246:249], v[48:63]
	v_exp_f32_e32 v88, v88
	v_exp_f32_e32 v89, v89
	ds_read_b64_tr_b16 v[246:247], v151 offset:9728
	ds_read_b64_tr_b16 v[248:249], v151 offset:11776
	s_waitcnt lgkmcnt(12)
	v_mfma_f32_32x32x16_bf16 v[32:47], v[182:185], v[250:253], v[32:47]
	v_exp_f32_e32 v90, v90
	v_exp_f32_e32 v91, v91
	v_add_f32_e32 v234, v234, v88
	ds_read_b64_tr_b16 v[250:251], v151 offset:12288
	ds_read_b64_tr_b16 v[252:253], v151 offset:14336
	s_waitcnt lgkmcnt(12)
	v_mfma_f32_32x32x16_bf16 v[16:31], v[182:185], v[152:155], v[16:31]
	v_exp_f32_e32 v92, v92
	v_exp_f32_e32 v93, v93
	v_add_f32_e32 v235, v235, v89
	v_add_f32_e32 v234, v234, v90
	ds_read_b64_tr_b16 v[152:153], v151 offset:12800
	ds_read_b64_tr_b16 v[154:155], v151 offset:14848
	s_waitcnt lgkmcnt(12)
	v_mfma_f32_32x32x16_bf16 v[0:15], v[182:185], v[226:229], v[0:15]
	v_exp_f32_e32 v94, v94
	v_exp_f32_e32 v95, v95
	v_add_f32_e32 v235, v235, v91
	v_add_f32_e32 v234, v234, v92
	ds_read_b64_tr_b16 v[226:227], v151 offset:13312
	ds_read_b64_tr_b16 v[228:229], v151 offset:15360
	s_waitcnt lgkmcnt(12)
	v_mfma_f32_32x32x16_bf16 v[48:63], v[186:189], v[230:233], v[48:63]
	v_add_f32_e32 v235, v235, v93
	v_add_f32_e32 v234, v234, v94
	v_add_f32_e32 v235, v235, v95
	v_cvt_pk_bf16_f32 v190, v88, v89
	v_cvt_pk_bf16_f32 v192, v92, v93
	ds_read_b64_tr_b16 v[230:231], v151 offset:13824
	ds_read_b64_tr_b16 v[232:233], v151 offset:15872
	s_waitcnt lgkmcnt(12)
	v_mfma_f32_32x32x16_bf16 v[32:47], v[186:189], v[238:241], v[32:47]
	s_waitcnt vmcnt(0)
	s_barrier
	s_add_i32 s62, s62, 0x4000
	s_cmp_ge_u32 s62, 0x14000
	s_cselect_b32 s69, 0x14000, 0
	s_sub_i32 s62, s62, s69
	v_add_u32_e32 v151, s62, v140
	v_cvt_pk_bf16_f32 v191, v90, v91
	v_cvt_pk_bf16_f32 v193, v94, v95
	v_permlane32_swap_b32_e32 v190, v192
	s_nop 0
	v_permlane32_swap_b32_e32 v191, v193
	s_waitcnt lgkmcnt(10)
	v_mfma_f32_32x32x16_bf16 v[16:31], v[186:189], v[242:245], v[16:31]
	v_exp_f32_e32 v96, v96
	v_exp_f32_e32 v97, v97
	s_waitcnt lgkmcnt(8)
	v_mfma_f32_32x32x16_bf16 v[0:15], v[186:189], v[246:249], v[0:15]
	v_exp_f32_e32 v98, v98
	v_exp_f32_e32 v99, v99
	v_add_f32_e32 v234, v234, v96
	s_waitcnt lgkmcnt(6)
	v_mfma_f32_32x32x16_bf16 v[48:63], v[190:193], v[250:253], v[48:63]
	v_exp_f32_e32 v100, v100
	v_exp_f32_e32 v101, v101
	v_add_f32_e32 v235, v235, v97
	v_add_f32_e32 v234, v234, v98
	s_waitcnt lgkmcnt(4)
	v_mfma_f32_32x32x16_bf16 v[32:47], v[190:193], v[152:155], v[32:47]
	v_exp_f32_e32 v102, v102
	v_exp_f32_e32 v103, v103
	v_add_f32_e32 v235, v235, v99
	v_add_f32_e32 v234, v234, v100
	s_waitcnt lgkmcnt(2)
	v_mfma_f32_32x32x16_bf16 v[16:31], v[190:193], v[226:229], v[16:31]
	v_add_f32_e32 v235, v235, v101
	v_add_f32_e32 v234, v234, v102
	v_add_f32_e32 v235, v235, v103
	v_cvt_pk_bf16_f32 v178, v96, v97
	v_cvt_pk_bf16_f32 v180, v100, v101
	s_waitcnt lgkmcnt(0)
	v_mfma_f32_32x32x16_bf16 v[0:15], v[190:193], v[230:233], v[0:15]
	v_cvt_pk_bf16_f32 v179, v98, v99
	v_cvt_pk_bf16_f32 v181, v102, v103
	v_permlane32_swap_b32_e32 v178, v180
	s_nop 0
	v_permlane32_swap_b32_e32 v179, v181
	v_exp_f32_e32 v104, v104
	v_exp_f32_e32 v105, v105
	v_exp_f32_e32 v106, v106
	v_exp_f32_e32 v107, v107
	v_add_f32_e32 v234, v234, v104
	ds_read_b64_tr_b16 v[226:227], v151 offset:0
	ds_read_b64_tr_b16 v[228:229], v151 offset:2048
	v_exp_f32_e32 v108, v108
	v_exp_f32_e32 v109, v109
	v_add_f32_e32 v235, v235, v105
	v_add_f32_e32 v234, v234, v106
	ds_read_b64_tr_b16 v[230:231], v151 offset:512
	ds_read_b64_tr_b16 v[232:233], v151 offset:2560
	v_exp_f32_e32 v110, v110
	v_exp_f32_e32 v111, v111
	v_add_f32_e32 v235, v235, v107
	v_add_f32_e32 v234, v234, v108
	ds_read_b64_tr_b16 v[238:239], v151 offset:1024
	ds_read_b64_tr_b16 v[240:241], v151 offset:3072
	v_add_f32_e32 v235, v235, v109
	v_add_f32_e32 v234, v234, v110
	v_add_f32_e32 v235, v235, v111
	v_cvt_pk_bf16_f32 v182, v104, v105
	v_cvt_pk_bf16_f32 v184, v108, v109
	ds_read_b64_tr_b16 v[242:243], v151 offset:1536
	ds_read_b64_tr_b16 v[244:245], v151 offset:3584
	v_cvt_pk_bf16_f32 v183, v106, v107
	v_cvt_pk_bf16_f32 v185, v110, v111
	v_permlane32_swap_b32_e32 v182, v184
	ds_read_b64_tr_b16 v[246:247], v151 offset:4096
	ds_read_b64_tr_b16 v[248:249], v151 offset:6144
	v_permlane32_swap_b32_e32 v183, v185
	v_exp_f32_e32 v162, v162
	v_exp_f32_e32 v163, v163
	ds_read_b64_tr_b16 v[250:251], v151 offset:4608
	ds_read_b64_tr_b16 v[252:253], v151 offset:6656
	v_exp_f32_e32 v164, v164
	v_exp_f32_e32 v165, v165
	v_add_f32_e32 v234, v234, v162
	ds_read_b64_tr_b16 v[152:153], v151 offset:5120
	ds_read_b64_tr_b16 v[154:155], v151 offset:7168
	s_waitcnt lgkmcnt(12)
	v_mfma_f32_32x32x16_bf16 v[48:63], v[178:181], v[226:229], v[48:63]
	v_exp_f32_e32 v166, v166
	v_exp_f32_e32 v167, v167
	v_add_f32_e32 v235, v235, v163
	v_add_f32_e32 v234, v234, v164
	ds_read_b64_tr_b16 v[226:227], v151 offset:5632
	ds_read_b64_tr_b16 v[228:229], v151 offset:7680
	s_waitcnt lgkmcnt(12)
	v_mfma_f32_32x32x16_bf16 v[32:47], v[178:181], v[230:233], v[32:47]
	v_exp_f32_e32 v168, v168
	v_exp_f32_e32 v169, v169
	v_add_f32_e32 v235, v235, v165
	v_add_f32_e32 v234, v234, v166
	ds_read_b64_tr_b16 v[230:231], v151 offset:8192
	ds_read_b64_tr_b16 v[232:233], v151 offset:10240
	s_waitcnt lgkmcnt(12)
	v_mfma_f32_32x32x16_bf16 v[16:31], v[178:181], v[238:241], v[16:31]
	v_add_f32_e32 v235, v235, v167
	v_add_f32_e32 v234, v234, v168
	v_add_f32_e32 v235, v235, v169
	v_cvt_pk_bf16_f32 v186, v162, v163
	v_cvt_pk_bf16_f32 v188, v166, v167
	ds_read_b64_tr_b16 v[238:239], v151 offset:8704
	ds_read_b64_tr_b16 v[240:241], v151 offset:10752
	s_waitcnt lgkmcnt(12)
	v_mfma_f32_32x32x16_bf16 v[0:15], v[178:181], v[242:245], v[0:15]
	v_cvt_pk_bf16_f32 v187, v164, v165
	v_cvt_pk_bf16_f32 v189, v168, v169
	v_permlane32_swap_b32_e32 v186, v188
	ds_read_b64_tr_b16 v[242:243], v151 offset:9216
	ds_read_b64_tr_b16 v[244:245], v151 offset:11264
	v_permlane32_swap_b32_e32 v187, v189
	s_waitcnt lgkmcnt(12)
	v_mfma_f32_32x32x16_bf16 v[48:63], v[182:185], v[246:249], v[48:63]
	v_exp_f32_e32 v170, v170
	v_exp_f32_e32 v171, v171
	ds_read_b64_tr_b16 v[246:247], v151 offset:9728
	ds_read_b64_tr_b16 v[248:249], v151 offset:11776
	s_waitcnt lgkmcnt(12)
	v_mfma_f32_32x32x16_bf16 v[32:47], v[182:185], v[250:253], v[32:47]
	v_exp_f32_e32 v172, v172
	v_exp_f32_e32 v173, v173
	v_add_f32_e32 v234, v234, v170
	ds_read_b64_tr_b16 v[250:251], v151 offset:12288
	ds_read_b64_tr_b16 v[252:253], v151 offset:14336
	s_waitcnt lgkmcnt(12)
	v_mfma_f32_32x32x16_bf16 v[16:31], v[182:185], v[152:155], v[16:31]
	v_exp_f32_e32 v174, v174
	v_exp_f32_e32 v175, v175
	v_add_f32_e32 v235, v235, v171
	v_add_f32_e32 v234, v234, v172
	ds_read_b64_tr_b16 v[152:153], v151 offset:12800
	ds_read_b64_tr_b16 v[154:155], v151 offset:14848
	s_waitcnt lgkmcnt(12)
	v_mfma_f32_32x32x16_bf16 v[0:15], v[182:185], v[226:229], v[0:15]
	v_exp_f32_e32 v176, v176
	v_exp_f32_e32 v177, v177
	v_add_f32_e32 v235, v235, v173
	v_add_f32_e32 v234, v234, v174
	ds_read_b64_tr_b16 v[226:227], v151 offset:13312
	ds_read_b64_tr_b16 v[228:229], v151 offset:15360
	s_waitcnt lgkmcnt(12)
	v_mfma_f32_32x32x16_bf16 v[48:63], v[186:189], v[230:233], v[48:63]
	v_add_f32_e32 v235, v235, v175
	v_add_f32_e32 v234, v234, v176
	v_add_f32_e32 v235, v235, v177
	v_cvt_pk_bf16_f32 v190, v170, v171
	v_cvt_pk_bf16_f32 v192, v174, v175
	ds_read_b64_tr_b16 v[230:231], v151 offset:13824
	ds_read_b64_tr_b16 v[232:233], v151 offset:15872
	s_waitcnt lgkmcnt(12)
	v_mfma_f32_32x32x16_bf16 v[32:47], v[186:189], v[238:241], v[32:47]
	s_add_i32 s62, s62, 0x4000
	s_cmp_ge_u32 s62, 0x14000
	s_cselect_b32 s69, 0x14000, 0
	s_sub_i32 s62, s62, s69
	v_add_u32_e32 v151, s62, v140
	v_cvt_pk_bf16_f32 v191, v172, v173
	v_cvt_pk_bf16_f32 v193, v176, v177
	v_permlane32_swap_b32_e32 v190, v192
	s_nop 0
	v_permlane32_swap_b32_e32 v191, v193
	s_waitcnt lgkmcnt(10)
	v_mfma_f32_32x32x16_bf16 v[16:31], v[186:189], v[242:245], v[16:31]
	s_waitcnt lgkmcnt(8)
	v_mfma_f32_32x32x16_bf16 v[0:15], v[186:189], v[246:249], v[0:15]
	s_waitcnt lgkmcnt(6)
	v_mfma_f32_32x32x16_bf16 v[48:63], v[190:193], v[250:253], v[48:63]
	s_waitcnt lgkmcnt(4)
	v_mfma_f32_32x32x16_bf16 v[32:47], v[190:193], v[152:155], v[32:47]
	s_waitcnt lgkmcnt(2)
	v_mfma_f32_32x32x16_bf16 v[16:31], v[190:193], v[226:229], v[16:31]
	s_waitcnt lgkmcnt(0)
	v_mfma_f32_32x32x16_bf16 v[0:15], v[190:193], v[230:233], v[0:15]
	v_add_f32_e32 v68, v234, v235
	v_mov_b32_e32 v69, 0
	v_mov_b32_e32 v71, 0
	v_mov_b32_e32 v70, v68
	v_mov_b32_e32 v128, 0
	s_nop 0
	v_permlane32_swap_b32_e32 v68, v70
	s_and_b32 s4, s35, 0x3fffffc0
	s_lshl_b32 s4, s4, 2
	s_add_i32 s7, s4, 0
	s_add_i32 s7, s7, 0x24000
	s_setprio 0
	v_cmp_gt_u32_e32 vcc, 32, v131
	s_and_saveexec_b64 s[4:5], vcc
	v_pk_add_f32 v[64:65], v[68:69], v[70:71]
	v_lshl_add_u32 v66, v136, 2, s7
	v_add_f32_e32 v64, v128, v64
	v_add_f32_e32 v64, v64, v65
	ds_write_b32 v66, v64
	s_or_b64 exec, exec, s[4:5]
	s_waitcnt lgkmcnt(0)
	global_load_dword v65, v129, s[14:15]
	v_add_u32_e32 v64, s7, v130
	ds_read_b128 v[66:69], v64
	ds_read_b128 v[70:73], v64 offset:32
	s_lshl_b32 s4, s34, 14
	ds_read_b128 v[96:99], v64 offset:96
	s_add_i32 s10, s4, 0
	s_waitcnt lgkmcnt(0)
	v_rcp_f32_e32 v94, v66
	v_rcp_f32_e32 v92, v67
	v_rcp_f32_e32 v90, v68
	v_rcp_f32_e32 v88, v69
	ds_read_b128 v[66:69], v64 offset:64
	v_rcp_f32_e32 v86, v70
	v_rcp_f32_e32 v84, v71
	v_rcp_f32_e32 v82, v72
	v_rcp_f32_e32 v80, v73
	s_waitcnt lgkmcnt(0)
	v_rcp_f32_e32 v78, v66
	v_rcp_f32_e32 v76, v67
	v_rcp_f32_e32 v74, v68
	v_rcp_f32_e32 v72, v69
	v_rcp_f32_e32 v70, v96
	v_rcp_f32_e32 v68, v97
	v_rcp_f32_e32 v66, v98
	v_rcp_f32_e32 v64, v99
	s_cmp_eq_u32 s19, 0
	s_cselect_b64 s[4:5], -1, 0
	s_and_b64 vcc, exec, s[4:5]
	v_lshlrev_b32_e32 v73, 2, v136
	s_waitcnt vmcnt(0)
	s_barrier
	s_cbranch_vccnz .LBB0_326
	v_lshlrev_b32_e32 v67, 11, v137
	v_mul_f32_e32 v69, v94, v65
	v_add3_u32 v67, s10, v67, v73
	v_mul_f32_e32 v71, v48, v69
	v_mul_f32_e32 v75, v32, v69
	ds_write2_b32 v67, v71, v75 offset1:32
	v_mul_f32_e32 v71, v16, v69
	v_mul_f32_e32 v69, v0, v69
	ds_write2_b32 v67, v71, v69 offset0:64 offset1:96
	v_mul_f32_e32 v69, v92, v65
	v_mul_f32_e32 v71, v49, v69
	v_mul_f32_e32 v75, v33, v69
	ds_write2_b32 v67, v71, v75 offset0:128 offset1:160
	v_mul_f32_e32 v71, v17, v69
	v_mul_f32_e32 v69, v1, v69
	ds_write2_b32 v67, v71, v69 offset0:192 offset1:224
	v_mul_f32_e32 v69, v90, v65
	v_mul_f32_e32 v71, v50, v69
	v_mul_f32_e32 v75, v34, v69
	v_add_u32_e32 v77, 0x400, v67
	ds_write2_b32 v77, v71, v75 offset1:32
	v_mul_f32_e32 v71, v18, v69
	v_mul_f32_e32 v69, v2, v69
	ds_write2_b32 v77, v71, v69 offset0:64 offset1:96
	v_mul_f32_e32 v69, v88, v65
	v_mul_f32_e32 v71, v51, v69
	v_mul_f32_e32 v75, v35, v69
	ds_write2_b32 v77, v71, v75 offset0:128 offset1:160
	v_mul_f32_e32 v71, v19, v69
	v_mul_f32_e32 v69, v3, v69
	ds_write2_b32 v77, v71, v69 offset0:192 offset1:224
	v_mul_f32_e32 v69, v86, v65
	v_mul_f32_e32 v71, v52, v69
	v_mul_f32_e32 v75, v36, v69
	v_add_u32_e32 v77, 0x1000, v67
	ds_write2_b32 v77, v71, v75 offset1:32
	v_mul_f32_e32 v71, v20, v69
	v_mul_f32_e32 v69, v4, v69
	ds_write2_b32 v77, v71, v69 offset0:64 offset1:96
	v_mul_f32_e32 v69, v84, v65
	v_mul_f32_e32 v71, v53, v69
	v_mul_f32_e32 v75, v37, v69
	ds_write2_b32 v77, v71, v75 offset0:128 offset1:160
	v_mul_f32_e32 v71, v21, v69
	v_mul_f32_e32 v69, v5, v69
	ds_write2_b32 v77, v71, v69 offset0:192 offset1:224
	v_mul_f32_e32 v69, v82, v65
	v_mul_f32_e32 v71, v54, v69
	v_mul_f32_e32 v75, v38, v69
	v_add_u32_e32 v77, 0x1400, v67
	ds_write2_b32 v77, v71, v75 offset1:32
	v_mul_f32_e32 v71, v22, v69
	v_mul_f32_e32 v69, v6, v69
	ds_write2_b32 v77, v71, v69 offset0:64 offset1:96
	v_mul_f32_e32 v69, v80, v65
	v_mul_f32_e32 v71, v55, v69
	v_mul_f32_e32 v75, v39, v69
	ds_write2_b32 v77, v71, v75 offset0:128 offset1:160
	v_mul_f32_e32 v71, v23, v69
	v_mul_f32_e32 v69, v7, v69
	ds_write2_b32 v77, v71, v69 offset0:192 offset1:224
	v_mul_f32_e32 v69, v78, v65
	v_mul_f32_e32 v71, v56, v69
	v_mul_f32_e32 v75, v40, v69
	v_add_u32_e32 v77, 0x2000, v67
	ds_write2_b32 v77, v71, v75 offset1:32
	v_mul_f32_e32 v71, v24, v69
	v_mul_f32_e32 v69, v8, v69
	ds_write2_b32 v77, v71, v69 offset0:64 offset1:96
	v_mul_f32_e32 v69, v76, v65
	v_mul_f32_e32 v71, v57, v69
	v_mul_f32_e32 v75, v41, v69
	ds_write2_b32 v77, v71, v75 offset0:128 offset1:160
	v_mul_f32_e32 v71, v25, v69
	v_mul_f32_e32 v69, v9, v69
	ds_write2_b32 v77, v71, v69 offset0:192 offset1:224
	v_mul_f32_e32 v69, v74, v65
	v_mul_f32_e32 v71, v58, v69
	v_mul_f32_e32 v75, v42, v69
	v_add_u32_e32 v77, 0x2400, v67
	ds_write2_b32 v77, v71, v75 offset1:32
	v_mul_f32_e32 v71, v26, v69
	v_mul_f32_e32 v69, v10, v69
	ds_write2_b32 v77, v71, v69 offset0:64 offset1:96
	v_mul_f32_e32 v69, v72, v65
	v_mul_f32_e32 v71, v59, v69
	v_mul_f32_e32 v75, v43, v69
	ds_write2_b32 v77, v71, v75 offset0:128 offset1:160
	v_mul_f32_e32 v71, v27, v69
	v_mul_f32_e32 v69, v11, v69
	ds_write2_b32 v77, v71, v69 offset0:192 offset1:224
	v_mul_f32_e32 v69, v70, v65
	v_mul_f32_e32 v71, v60, v69
	v_mul_f32_e32 v75, v44, v69
	v_add_u32_e32 v77, 0x3000, v67
	ds_write2_b32 v77, v71, v75 offset1:32
	v_mul_f32_e32 v71, v28, v69
	v_mul_f32_e32 v69, v12, v69
	ds_write2_b32 v77, v71, v69 offset0:64 offset1:96
	v_mul_f32_e32 v69, v68, v65
	v_mul_f32_e32 v71, v61, v69
	v_mul_f32_e32 v75, v45, v69
	ds_write2_b32 v77, v71, v75 offset0:128 offset1:160
	v_mul_f32_e32 v71, v29, v69
	v_mul_f32_e32 v69, v13, v69
	ds_write2_b32 v77, v71, v69 offset0:192 offset1:224
	v_mul_f32_e32 v69, v66, v65
	v_mul_f32_e32 v71, v62, v69
	v_mul_f32_e32 v75, v46, v69
	v_add_u32_e32 v67, 0x3400, v67
	ds_write2_b32 v67, v71, v75 offset1:32
	v_mul_f32_e32 v71, v30, v69
	v_mul_f32_e32 v69, v14, v69
	v_mul_f32_e32 v65, v65, v64
	ds_write2_b32 v67, v71, v69 offset0:64 offset1:96
	v_mul_f32_e32 v69, v63, v65
	v_mul_f32_e32 v71, v47, v65
	ds_write2_b32 v67, v69, v71 offset0:128 offset1:160
	v_mul_f32_e32 v69, v31, v65
	v_mul_f32_e32 v65, v15, v65
	ds_write2_b32 v67, v69, v65 offset0:192 offset1:224

	.amdhsa_kernel _Z4mega6Params
		.amdhsa_group_segment_fixed_size 0
		.amdhsa_private_segment_fixed_size 0
		.amdhsa_kernarg_size 456
		.amdhsa_user_sgpr_count 2
		.amdhsa_user_sgpr_dispatch_ptr 0
		.amdhsa_user_sgpr_queue_ptr 0
		.amdhsa_user_sgpr_kernarg_segment_ptr 1
		.amdhsa_user_sgpr_dispatch_id 0
		.amdhsa_user_sgpr_kernarg_preload_length 0
		.amdhsa_user_sgpr_kernarg_preload_offset 0
		.amdhsa_user_sgpr_private_segment_size 0
		.amdhsa_uses_dynamic_stack 0
		.amdhsa_enable_private_segment 0
		.amdhsa_system_sgpr_workgroup_id_x 1
		.amdhsa_system_sgpr_workgroup_id_y 0
		.amdhsa_system_sgpr_workgroup_id_z 0
		.amdhsa_system_sgpr_workgroup_info 0
		.amdhsa_system_vgpr_workitem_id 2
		.amdhsa_next_free_vgpr 256
		.amdhsa_next_free_sgpr 98
		.amdhsa_accum_offset 256
		.amdhsa_reserve_vcc 1
		.amdhsa_float_round_mode_32 0
		.amdhsa_float_round_mode_16_64 0
		.amdhsa_float_denorm_mode_32 3
		.amdhsa_float_denorm_mode_16_64 3
		.amdhsa_dx10_clamp 1
		.amdhsa_ieee_mode 1
		.amdhsa_fp16_overflow 0
		.amdhsa_tg_split 0
		.amdhsa_exception_fp_ieee_invalid_op 0
		.amdhsa_exception_fp_denorm_src 0
		.amdhsa_exception_fp_ieee_div_zero 0
		.amdhsa_exception_fp_ieee_overflow 0
		.amdhsa_exception_fp_ieee_underflow 0
		.amdhsa_exception_fp_ieee_inexact 0
		.amdhsa_exception_int_div_zero 0
	.end_amdhsa_kernel

amdhsa.kernels:
  - .agpr_count:     0
    .args:
      - .offset:         0
        .size:           200
        .value_kind:     by_value
      - .offset:         200
        .size:           4
        .value_kind:     hidden_block_count_x
      - .offset:         204
        .size:           4
        .value_kind:     hidden_block_count_y
      - .offset:         208
        .size:           4
        .value_kind:     hidden_block_count_z
      - .offset:         212
        .size:           2
        .value_kind:     hidden_group_size_x
      - .offset:         214
        .size:           2
        .value_kind:     hidden_group_size_y
      - .offset:         216
        .size:           2
        .value_kind:     hidden_group_size_z
      - .offset:         218
        .size:           2
        .value_kind:     hidden_remainder_x
      - .offset:         220
        .size:           2
        .value_kind:     hidden_remainder_y
      - .offset:         222
        .size:           2
        .value_kind:     hidden_remainder_z
      - .offset:         240
        .size:           8
        .value_kind:     hidden_global_offset_x
      - .offset:         248
        .size:           8
        .value_kind:     hidden_global_offset_y
      - .offset:         256
        .size:           8
        .value_kind:     hidden_global_offset_z
      - .offset:         264
        .size:           2
        .value_kind:     hidden_grid_dims
      - .offset:         288
        .size:           8
        .value_kind:     hidden_multigrid_sync_arg
      - .offset:         320
        .size:           4
        .value_kind:     hidden_dynamic_lds_size
    .group_segment_fixed_size: 0
    .kernarg_segment_align: 8
    .kernarg_segment_size: 456
    .language:       OpenCL C
    .language_version:
      - 2
      - 0
    .max_flat_workgroup_size: 512
    .name:           _Z4mega6Params
    .private_segment_fixed_size: 0
    .sgpr_count:     104
    .sgpr_spill_count: 28
    .symbol:         _Z4mega6Params.kd
    .uniform_work_group_size: 1
    .uses_dynamic_stack: false
    .vgpr_count:     256
    .vgpr_spill_count: 0
    .wavefront_size: 64
